# nt hint also on the deferred bf16 weight-copy stores and on the GEMM3 epilogue stores (activations consumed a phase later)
# speedup vs baseline: 1.0076x; 1.0018x over previous
; #define GAS __attribute__((address_space(1)))
; #define LAS __attribute__((address_space(3)))
; __device__ __forceinline__ unsigned pk2(float lo, float hi) { return pg8::cvt_pk_bf16(lo, hi); }
; #define LDS_WAIT() asm volatile("s_waitcnt lgkmcnt(0)" ::: "memory")
; __device__ __forceinline__ void tr_store(const TrItem& t, const float (&tv)[32], LAS float* scr, int lane) {
;     const float* gp = t.gk ? t.gk + t.k0 + 32 * (lane >> 5) : nullptr; LAS unsigned* T = (LAS unsigned*)scr;
; #pragma unroll
;     for (int j = 0; j < 16; ++j) { float a = tv[2 * j], b = tv[2 * j + 1]; if (gp) { a *= gp[2 * j]; b *= gp[2 * j + 1]; } T[(16 * (lane >> 5) + j) * TR_P + (lane & 31)] = pk2(a, b); }
;     LDS_WAIT(); asm volatile("" ::: "memory");
;     const int c = lane & 7;
; #pragma unroll
;     for (int j = 0; j < 4; ++j) { const int n = (lane >> 3) + 8 * j; const LAS unsigned* s = T + (4 * c) * TR_P + n;
;         v4u o; o.x = s[0 * TR_P]; o.y = s[1 * TR_P]; o.z = s[2 * TR_P]; o.w = s[3 * TR_P];
;         *(GAS v4u*)(t.WT + (size_t)(t.drow + n) * t.K + t.k0 + 8 * c) = o; }
;     LDS_WAIT(); asm volatile("" ::: "memory");
.LBB0_755:
	v_cvt_pk_bf16_f32 v25, v72, v73
	ds_write_b32 v81, v25
	s_waitcnt lgkmcnt(0)
	ds_read2_b32 v[86:87], v76 offset1:8
	ds_read2_b32 v[70:71], v76 offset0:34 offset1:42
	ds_read2_b32 v[88:89], v76 offset0:68 offset1:76
	ds_read2_b32 v[72:73], v76 offset0:102 offset1:110
	v_add_u32_e32 v90, s49, v75
	v_ashrrev_i32_e32 v91, 31, v90
	v_lshlrev_b64 v[90:91], 13, v[90:91]
	v_lshl_add_u64 v[90:91], s[42:43], 0, v[90:91]
	s_lshl_b64 s[6:7], s[36:37], 1
	v_lshl_add_u64 v[90:91], v[90:91], 0, s[6:7]
	s_waitcnt lgkmcnt(3)
	v_mov_b32_e32 v82, v86
	s_waitcnt lgkmcnt(2)
	v_mov_b32_e32 v83, v70
	s_waitcnt lgkmcnt(1)
	v_mov_b32_e32 v84, v88
	s_waitcnt lgkmcnt(0)
	v_mov_b32_e32 v85, v72
	v_lshl_add_u64 v[90:91], v[90:91], 0, v[22:23]
	global_store_dwordx4 v[90:91], v[82:85], off nt
	v_mov_b32_e32 v70, v87
	v_mov_b32_e32 v72, v89
	v_add_u32_e32 v82, s49, v77
	v_ashrrev_i32_e32 v83, 31, v82
	v_lshlrev_b64 v[82:83], 13, v[82:83]
	v_lshl_add_u64 v[82:83], s[42:43], 0, v[82:83]
	v_lshl_add_u64 v[82:83], v[82:83], 0, s[6:7]
	v_lshl_add_u64 v[86:87], v[82:83], 0, v[22:23]
	ds_read2_b32 v[88:89], v76 offset0:16 offset1:24
	ds_read2_b32 v[82:83], v76 offset0:50 offset1:58
	ds_read2_b32 v[90:91], v76 offset0:84 offset1:92
	ds_read2_b32 v[84:85], v76 offset0:118 offset1:126
	global_store_dwordx4 v[86:87], v[70:73], off nt
	v_add_u32_e32 v86, s49, v78
	v_ashrrev_i32_e32 v87, 31, v86
	v_lshlrev_b64 v[86:87], 13, v[86:87]
	v_lshl_add_u64 v[86:87], s[42:43], 0, v[86:87]
	v_lshl_add_u64 v[86:87], v[86:87], 0, s[6:7]
	s_waitcnt lgkmcnt(3)
	v_mov_b32_e32 v70, v88
	s_waitcnt lgkmcnt(2)
	v_mov_b32_e32 v71, v82
	s_waitcnt lgkmcnt(1)
	v_mov_b32_e32 v72, v90
	s_waitcnt lgkmcnt(0)
	v_mov_b32_e32 v73, v84
	v_lshl_add_u64 v[86:87], v[86:87], 0, v[22:23]
	global_store_dwordx4 v[86:87], v[70:73], off nt
	v_mov_b32_e32 v82, v89
	v_mov_b32_e32 v84, v91
	v_add_u32_e32 v70, s49, v79
	v_ashrrev_i32_e32 v71, 31, v70
	v_lshlrev_b64 v[70:71], 13, v[70:71]
	v_lshl_add_u64 v[70:71], s[42:43], 0, v[70:71]
	v_lshl_add_u64 v[70:71], v[70:71], 0, s[6:7]
	v_lshl_add_u64 v[70:71], v[70:71], 0, v[22:23]
	global_store_dwordx4 v[70:71], v[82:85], off nt
	s_waitcnt lgkmcnt(0)
	s_add_i32 s47, s47, 2

; #define GAS __attribute__((address_space(1)))
; #define LAS __attribute__((address_space(3)))
; __device__ __forceinline__ unsigned pk2(float lo, float hi) { return pg8::cvt_pk_bf16(lo, hi); }
; #define LDS_WAIT() asm volatile("s_waitcnt lgkmcnt(0)" ::: "memory")
; __device__ __forceinline__ void tr_store(const TrItem& t, const float (&tv)[32], LAS float* scr, int lane) {
;     const float* gp = t.gk ? t.gk + t.k0 + 32 * (lane >> 5) : nullptr; LAS unsigned* T = (LAS unsigned*)scr;
; #pragma unroll
;     for (int j = 0; j < 16; ++j) { float a = tv[2 * j], b = tv[2 * j + 1]; if (gp) { a *= gp[2 * j]; b *= gp[2 * j + 1]; } T[(16 * (lane >> 5) + j) * TR_P + (lane & 31)] = pk2(a, b); }
;     LDS_WAIT(); asm volatile("" ::: "memory");
;     const int c = lane & 7;
; #pragma unroll
;     for (int j = 0; j < 4; ++j) { const int n = (lane >> 3) + 8 * j; const LAS unsigned* s = T + (4 * c) * TR_P + n;
;         v4u o; o.x = s[0 * TR_P]; o.y = s[1 * TR_P]; o.z = s[2 * TR_P]; o.w = s[3 * TR_P];
;         *(GAS v4u*)(t.WT + (size_t)(t.drow + n) * t.K + t.k0 + 8 * c) = o; }
;     LDS_WAIT(); asm volatile("" ::: "memory");
.LBB0_856:
	s_nop 0
	v_cvt_pk_bf16_f32 v25, v72, v73
	ds_write_b32 v81, v25
	s_waitcnt lgkmcnt(0)
	ds_read2_b32 v[86:87], v76 offset1:8
	ds_read2_b32 v[70:71], v76 offset0:34 offset1:42
	ds_read2_b32 v[88:89], v76 offset0:68 offset1:76
	ds_read2_b32 v[72:73], v76 offset0:102 offset1:110
	v_add_u32_e32 v90, s46, v75
	v_ashrrev_i32_e32 v91, 31, v90
	v_lshlrev_b64 v[90:91], 13, v[90:91]
	v_lshl_add_u64 v[90:91], s[30:31], 0, v[90:91]
	s_lshl_b64 s[8:9], s[26:27], 1
	v_lshl_add_u64 v[90:91], v[90:91], 0, s[8:9]
	s_waitcnt lgkmcnt(3)
	v_mov_b32_e32 v82, v86
	s_waitcnt lgkmcnt(2)
	v_mov_b32_e32 v83, v70
	s_waitcnt lgkmcnt(1)
	v_mov_b32_e32 v84, v88
	s_waitcnt lgkmcnt(0)
	v_mov_b32_e32 v85, v72
	v_lshl_add_u64 v[90:91], v[90:91], 0, v[22:23]
	global_store_dwordx4 v[90:91], v[82:85], off nt
	v_mov_b32_e32 v70, v87
	v_mov_b32_e32 v72, v89
	v_add_u32_e32 v82, s46, v77
	v_ashrrev_i32_e32 v83, 31, v82
	v_lshlrev_b64 v[82:83], 13, v[82:83]
	v_lshl_add_u64 v[82:83], s[30:31], 0, v[82:83]
	v_lshl_add_u64 v[82:83], v[82:83], 0, s[8:9]
	v_lshl_add_u64 v[86:87], v[82:83], 0, v[22:23]
	ds_read2_b32 v[88:89], v76 offset0:16 offset1:24
	ds_read2_b32 v[82:83], v76 offset0:50 offset1:58
	ds_read2_b32 v[90:91], v76 offset0:84 offset1:92
	ds_read2_b32 v[84:85], v76 offset0:118 offset1:126
	global_store_dwordx4 v[86:87], v[70:73], off nt
	v_add_u32_e32 v86, s46, v78
	v_ashrrev_i32_e32 v87, 31, v86
	v_lshlrev_b64 v[86:87], 13, v[86:87]
	v_lshl_add_u64 v[86:87], s[30:31], 0, v[86:87]
	v_lshl_add_u64 v[86:87], v[86:87], 0, s[8:9]
	s_waitcnt lgkmcnt(3)
	v_mov_b32_e32 v70, v88
	s_waitcnt lgkmcnt(2)
	v_mov_b32_e32 v71, v82
	s_waitcnt lgkmcnt(1)
	v_mov_b32_e32 v72, v90
	s_waitcnt lgkmcnt(0)
	v_mov_b32_e32 v73, v84
	v_lshl_add_u64 v[86:87], v[86:87], 0, v[22:23]
	global_store_dwordx4 v[86:87], v[70:73], off nt
	v_mov_b32_e32 v82, v89
	v_mov_b32_e32 v84, v91
	v_add_u32_e32 v70, s46, v79
	v_ashrrev_i32_e32 v71, 31, v70
	v_lshlrev_b64 v[70:71], 13, v[70:71]
	v_lshl_add_u64 v[70:71], s[30:31], 0, v[70:71]
	v_lshl_add_u64 v[70:71], v[70:71], 0, s[8:9]
	v_lshl_add_u64 v[70:71], v[70:71], 0, v[22:23]
	global_store_dwordx4 v[70:71], v[82:85], off nt
	s_waitcnt lgkmcnt(0)
	s_and_b64 vcc, exec, s[6:7]
	s_mov_b64 s[8:9], -1
	s_cbranch_vccnz .LBB0_756
	s_add_i32 s27, s29, 2
	s_cmp_lt_u32 s47, 14
	s_cselect_b64 s[6:7], -1, 0
	s_cmp_lt_i32 s27, 0xe000
	s_cselect_b64 s[8:9], -1, 0
	s_and_b64 s[6:7], s[6:7], s[8:9]
	s_xor_b64 s[8:9], s[6:7], -1
	s_and_b64 vcc, exec, s[8:9]
	s_cbranch_vccnz .LBB0_862
	s_cmpk_gt_i32 s27, 0x1fff
	s_cbranch_scc0 .LBB0_860
	s_add_i32 s5, s27, 0xe000
	s_and_b32 s18, s5, 0xffff
	s_mul_i32 s18, s18, 0xaaab
	s_lshr_b32 s18, s18, 25
	s_mul_i32 s19, s18, 0x300
	s_sub_i32 s19, s5, s19
	s_lshl_b32 s5, s19, 5
	s_and_b32 s5, s5, 0xffe0
	s_and_b32 s19, s19, 0xffff
	s_add_i32 s24, s5, 0xffffd000
	s_cmpk_lt_u32 s19, 0x180
	s_cselect_b32 s19, s5, s24
	s_cselect_b32 s24, 0, 0x80
	s_lshl_b32 s25, s19, 1
	s_and_b32 s19, s19, 0x60
	s_and_b32 s25, s25, 0xffffff00
	s_or_b32 s19, s19, s24
	s_or_b32 s46, s19, s25
	s_lshl_b32 s26, s18, 6
	s_mov_b64 s[24:25], s[22:23]
	s_mov_b64 s[18:19], s[14:15]
	s_movk_i32 s28, 0x6000
	s_mov_b64 s[30:31], s[10:11]
	s_cbranch_execz .LBB0_861
	s_branch .LBB0_862

; #define GAS __attribute__((address_space(1)))
; #define LAS __attribute__((address_space(3)))
; __device__ __forceinline__ unsigned pk2(float lo, float hi) { return pg8::cvt_pk_bf16(lo, hi); }
; #define LDS_WAIT() asm volatile("s_waitcnt lgkmcnt(0)" ::: "memory")
; __device__ __forceinline__ void tr_store(const TrItem& t, const float (&tv)[32], LAS float* scr, int lane) {
;     const float* gp = t.gk ? t.gk + t.k0 + 32 * (lane >> 5) : nullptr; LAS unsigned* T = (LAS unsigned*)scr;
; #pragma unroll
;     for (int j = 0; j < 16; ++j) { float a = tv[2 * j], b = tv[2 * j + 1]; if (gp) { a *= gp[2 * j]; b *= gp[2 * j + 1]; } T[(16 * (lane >> 5) + j) * TR_P + (lane & 31)] = pk2(a, b); }
;     LDS_WAIT(); asm volatile("" ::: "memory");
;     const int c = lane & 7;
; #pragma unroll
;     for (int j = 0; j < 4; ++j) { const int n = (lane >> 3) + 8 * j; const LAS unsigned* s = T + (4 * c) * TR_P + n;
;         v4u o; o.x = s[0 * TR_P]; o.y = s[1 * TR_P]; o.z = s[2 * TR_P]; o.w = s[3 * TR_P];
;         *(GAS v4u*)(t.WT + (size_t)(t.drow + n) * t.K + t.k0 + 8 * c) = o; }
;     LDS_WAIT(); asm volatile("" ::: "memory");
.LBB0_1480:
	s_nop 0
	v_cvt_pk_bf16_f32 v1, v76, v77
	ds_write_b32 v85, v1
	s_waitcnt lgkmcnt(0)
	ds_read2_b32 v[90:91], v80 offset1:8
	ds_read2_b32 v[74:75], v80 offset0:34 offset1:42
	ds_read2_b32 v[92:93], v80 offset0:68 offset1:76
	ds_read2_b32 v[76:77], v80 offset0:102 offset1:110
	v_add_u32_e32 v94, s57, v79
	v_ashrrev_i32_e32 v95, 31, v94
	v_lshlrev_b64 v[94:95], 13, v[94:95]
	v_lshl_add_u64 v[94:95], s[44:45], 0, v[94:95]
	s_lshl_b64 s[8:9], s[38:39], 1
	v_lshl_add_u64 v[94:95], v[94:95], 0, s[8:9]
	v_mov_b32_e32 v73, v3
	s_waitcnt lgkmcnt(3)
	v_mov_b32_e32 v86, v90
	s_waitcnt lgkmcnt(2)
	v_mov_b32_e32 v87, v74
	s_waitcnt lgkmcnt(1)
	v_mov_b32_e32 v88, v92
	s_waitcnt lgkmcnt(0)
	v_mov_b32_e32 v89, v76
	v_lshl_add_u64 v[94:95], v[94:95], 0, v[72:73]
	global_store_dwordx4 v[94:95], v[86:89], off nt
	v_mov_b32_e32 v74, v91
	v_mov_b32_e32 v76, v93
	v_add_u32_e32 v86, s57, v81
	v_ashrrev_i32_e32 v87, 31, v86
	v_lshlrev_b64 v[86:87], 13, v[86:87]
	v_lshl_add_u64 v[86:87], s[44:45], 0, v[86:87]
	v_lshl_add_u64 v[86:87], v[86:87], 0, s[8:9]
	v_lshl_add_u64 v[90:91], v[86:87], 0, v[72:73]
	ds_read2_b32 v[92:93], v80 offset0:16 offset1:24
	ds_read2_b32 v[86:87], v80 offset0:50 offset1:58
	ds_read2_b32 v[94:95], v80 offset0:84 offset1:92
	ds_read2_b32 v[88:89], v80 offset0:118 offset1:126
	global_store_dwordx4 v[90:91], v[74:77], off nt
	v_add_u32_e32 v90, s57, v82
	v_ashrrev_i32_e32 v91, 31, v90
	v_lshlrev_b64 v[90:91], 13, v[90:91]
	v_lshl_add_u64 v[90:91], s[44:45], 0, v[90:91]
	v_lshl_add_u64 v[90:91], v[90:91], 0, s[8:9]
	s_waitcnt lgkmcnt(3)
	v_mov_b32_e32 v74, v92
	s_waitcnt lgkmcnt(2)
	v_mov_b32_e32 v75, v86
	s_waitcnt lgkmcnt(1)
	v_mov_b32_e32 v76, v94
	s_waitcnt lgkmcnt(0)
	v_mov_b32_e32 v77, v88
	v_lshl_add_u64 v[90:91], v[90:91], 0, v[72:73]
	global_store_dwordx4 v[90:91], v[74:77], off nt
	v_mov_b32_e32 v86, v93
	v_mov_b32_e32 v88, v95
	v_add_u32_e32 v74, s57, v83
	v_ashrrev_i32_e32 v75, 31, v74
	v_lshlrev_b64 v[74:75], 13, v[74:75]
	v_lshl_add_u64 v[74:75], s[44:45], 0, v[74:75]
	v_lshl_add_u64 v[74:75], v[74:75], 0, s[8:9]
	v_lshl_add_u64 v[74:75], v[74:75], 0, v[72:73]
	global_store_dwordx4 v[74:75], v[86:89], off nt
	s_waitcnt lgkmcnt(0)
	s_and_b64 vcc, exec, s[6:7]
	s_mov_b64 s[8:9], -1
	s_cbranch_vccnz .LBB0_1380
	s_add_i32 s27, s27, 2
	s_cmp_lt_u32 s61, 14
	s_cselect_b64 s[6:7], -1, 0
	s_cmp_lt_i32 s27, 0xe000
	s_cselect_b64 s[8:9], -1, 0
	s_and_b64 s[6:7], s[6:7], s[8:9]
	s_xor_b64 s[8:9], s[6:7], -1
	s_and_b64 vcc, exec, s[8:9]
	s_cbranch_vccnz .LBB0_1486
	s_cmpk_gt_i32 s27, 0x1fff
	s_cbranch_scc0 .LBB0_1484
	s_add_i32 s14, s27, 0xe000
	s_and_b32 s15, s14, 0xffff
	s_mul_i32 s15, s15, 0xaaab
	s_lshr_b32 s15, s15, 25
	s_mul_i32 s29, s15, 0x300
	s_sub_i32 s14, s14, s29
	s_lshl_b32 s29, s14, 5
	s_and_b32 s55, s29, 0xffe0
	s_and_b32 s14, s14, 0xffff
	s_add_i32 s29, s55, 0xffffd000
	s_cmpk_lt_u32 s14, 0x180
	s_cselect_b32 s14, s55, s29
	s_cselect_b32 s29, 0, 0x80
	s_lshl_b32 s30, s14, 1
	s_and_b32 s14, s14, 0x60
	s_and_b32 s30, s30, 0xffffff00
	s_or_b32 s14, s14, s29
	s_or_b32 s57, s14, s30
	s_lshl_b32 s38, s15, 6
	s_mov_b64 s[30:31], s[46:47]
	s_mov_b64 s[36:37], s[18:19]
	s_movk_i32 s40, 0x6000
	s_mov_b64 s[44:45], s[50:51]
	s_cbranch_execz .LBB0_1485
	s_branch .LBB0_1486

; #define GAS __attribute__((address_space(1)))
; #define LAS __attribute__((address_space(3)))
; __device__ __forceinline__ unsigned pk2(float lo, float hi) { return pg8::cvt_pk_bf16(lo, hi); }
; #define LDS_WAIT() asm volatile("s_waitcnt lgkmcnt(0)" ::: "memory")
; __device__ __forceinline__ void tr_store(const TrItem& t, const float (&tv)[32], LAS float* scr, int lane) {
;     const float* gp = t.gk ? t.gk + t.k0 + 32 * (lane >> 5) : nullptr; LAS unsigned* T = (LAS unsigned*)scr;
; #pragma unroll
;     for (int j = 0; j < 16; ++j) { float a = tv[2 * j], b = tv[2 * j + 1]; if (gp) { a *= gp[2 * j]; b *= gp[2 * j + 1]; } T[(16 * (lane >> 5) + j) * TR_P + (lane & 31)] = pk2(a, b); }
;     LDS_WAIT(); asm volatile("" ::: "memory");
;     const int c = lane & 7;
; #pragma unroll
;     for (int j = 0; j < 4; ++j) { const int n = (lane >> 3) + 8 * j; const LAS unsigned* s = T + (4 * c) * TR_P + n;
;         v4u o; o.x = s[0 * TR_P]; o.y = s[1 * TR_P]; o.z = s[2 * TR_P]; o.w = s[3 * TR_P];
;         *(GAS v4u*)(t.WT + (size_t)(t.drow + n) * t.K + t.k0 + 8 * c) = o; }
;     LDS_WAIT(); asm volatile("" ::: "memory");
.LBB0_1582:
	s_nop 0
	v_cvt_pk_bf16_f32 v1, v76, v77
	ds_write_b32 v85, v1
	s_waitcnt lgkmcnt(0)
	ds_read2_b32 v[90:91], v80 offset1:8
	ds_read2_b32 v[74:75], v80 offset0:34 offset1:42
	ds_read2_b32 v[92:93], v80 offset0:68 offset1:76
	ds_read2_b32 v[76:77], v80 offset0:102 offset1:110
	v_add_u32_e32 v94, s54, v79
	v_ashrrev_i32_e32 v95, 31, v94
	v_lshlrev_b64 v[94:95], 13, v[94:95]
	v_lshl_add_u64 v[94:95], s[34:35], 0, v[94:95]
	s_lshl_b64 s[6:7], s[26:27], 1
	v_lshl_add_u64 v[94:95], v[94:95], 0, s[6:7]
	v_mov_b32_e32 v73, v3
	s_waitcnt lgkmcnt(3)
	v_mov_b32_e32 v86, v90
	s_waitcnt lgkmcnt(2)
	v_mov_b32_e32 v87, v74
	s_waitcnt lgkmcnt(1)
	v_mov_b32_e32 v88, v92
	s_waitcnt lgkmcnt(0)
	v_mov_b32_e32 v89, v76
	v_lshl_add_u64 v[94:95], v[94:95], 0, v[72:73]
	global_store_dwordx4 v[94:95], v[86:89], off nt
	v_mov_b32_e32 v74, v91
	v_mov_b32_e32 v76, v93
	v_add_u32_e32 v86, s54, v81
	v_ashrrev_i32_e32 v87, 31, v86
	v_lshlrev_b64 v[86:87], 13, v[86:87]
	v_lshl_add_u64 v[86:87], s[34:35], 0, v[86:87]
	v_lshl_add_u64 v[86:87], v[86:87], 0, s[6:7]
	v_lshl_add_u64 v[90:91], v[86:87], 0, v[72:73]
	ds_read2_b32 v[92:93], v80 offset0:16 offset1:24
	ds_read2_b32 v[86:87], v80 offset0:50 offset1:58
	ds_read2_b32 v[94:95], v80 offset0:84 offset1:92
	ds_read2_b32 v[88:89], v80 offset0:118 offset1:126
	global_store_dwordx4 v[90:91], v[74:77], off nt
	v_add_u32_e32 v90, s54, v82
	v_ashrrev_i32_e32 v91, 31, v90
	v_lshlrev_b64 v[90:91], 13, v[90:91]
	v_lshl_add_u64 v[90:91], s[34:35], 0, v[90:91]
	v_lshl_add_u64 v[90:91], v[90:91], 0, s[6:7]
	s_waitcnt lgkmcnt(3)
	v_mov_b32_e32 v74, v92
	s_waitcnt lgkmcnt(2)
	v_mov_b32_e32 v75, v86
	s_waitcnt lgkmcnt(1)
	v_mov_b32_e32 v76, v94
	s_waitcnt lgkmcnt(0)
	v_mov_b32_e32 v77, v88
	v_lshl_add_u64 v[90:91], v[90:91], 0, v[72:73]
	global_store_dwordx4 v[90:91], v[74:77], off nt
	v_mov_b32_e32 v86, v93
	v_mov_b32_e32 v88, v95
	v_add_u32_e32 v74, s54, v83
	v_ashrrev_i32_e32 v75, 31, v74
	v_lshlrev_b64 v[74:75], 13, v[74:75]
	v_lshl_add_u64 v[74:75], s[34:35], 0, v[74:75]
	v_lshl_add_u64 v[74:75], v[74:75], 0, s[6:7]
	v_lshl_add_u64 v[74:75], v[74:75], 0, v[72:73]
	global_store_dwordx4 v[74:75], v[86:89], off nt
	s_waitcnt lgkmcnt(0)
	s_add_i32 s61, s61, 2
	s_and_b64 vcc, exec, s[8:9]
	s_cbranch_vccz .LBB0_1381
	s_branch .LBB0_1303

; #define GAS __attribute__((address_space(1)))
; #define LAS __attribute__((address_space(3)))
; __device__ __forceinline__ unsigned pk2(float lo, float hi) { return pg8::cvt_pk_bf16(lo, hi); }
; #define LDS_WAIT() asm volatile("s_waitcnt lgkmcnt(0)" ::: "memory")
; __device__ __forceinline__ void tr_store(const TrItem& t, const float (&tv)[32], LAS float* scr, int lane) {
;     const float* gp = t.gk ? t.gk + t.k0 + 32 * (lane >> 5) : nullptr; LAS unsigned* T = (LAS unsigned*)scr;
; #pragma unroll
;     for (int j = 0; j < 16; ++j) { float a = tv[2 * j], b = tv[2 * j + 1]; if (gp) { a *= gp[2 * j]; b *= gp[2 * j + 1]; } T[(16 * (lane >> 5) + j) * TR_P + (lane & 31)] = pk2(a, b); }
;     LDS_WAIT(); asm volatile("" ::: "memory");
;     const int c = lane & 7;
; #pragma unroll
;     for (int j = 0; j < 4; ++j) { const int n = (lane >> 3) + 8 * j; const LAS unsigned* s = T + (4 * c) * TR_P + n;
;         v4u o; o.x = s[0 * TR_P]; o.y = s[1 * TR_P]; o.z = s[2 * TR_P]; o.w = s[3 * TR_P];
;         *(GAS v4u*)(t.WT + (size_t)(t.drow + n) * t.K + t.k0 + 8 * c) = o; }
;     LDS_WAIT(); asm volatile("" ::: "memory");
; }
.LBB0_2135:
	s_nop 0
	v_cvt_pk_bf16_f32 v1, v76, v77
	ds_write_b32 v84, v1
	s_waitcnt lgkmcnt(0)
	ds_read2_b32 v[90:91], v79 offset1:8
	ds_read2_b32 v[74:75], v79 offset0:34 offset1:42
	ds_read2_b32 v[92:93], v79 offset0:68 offset1:76
	ds_read2_b32 v[76:77], v79 offset0:102 offset1:110
	v_add_u32_e32 v94, s52, v78
	v_ashrrev_i32_e32 v95, 31, v94
	v_lshlrev_b64 v[94:95], 13, v[94:95]
	v_lshl_add_u64 v[94:95], s[40:41], 0, v[94:95]
	s_lshl_b64 s[8:9], s[36:37], 1
	v_lshl_add_u64 v[94:95], v[94:95], 0, s[8:9]
	v_mov_b32_e32 v73, v3
	s_waitcnt lgkmcnt(3)
	v_mov_b32_e32 v86, v90
	s_waitcnt lgkmcnt(2)
	v_mov_b32_e32 v87, v74
	s_waitcnt lgkmcnt(1)
	v_mov_b32_e32 v88, v92
	s_waitcnt lgkmcnt(0)
	v_mov_b32_e32 v89, v76
	v_lshl_add_u64 v[94:95], v[94:95], 0, v[72:73]
	global_store_dwordx4 v[94:95], v[86:89], off nt
	v_mov_b32_e32 v74, v91
	v_mov_b32_e32 v76, v93
	v_add_u32_e32 v86, s52, v80
	v_ashrrev_i32_e32 v87, 31, v86
	v_lshlrev_b64 v[86:87], 13, v[86:87]
	v_lshl_add_u64 v[86:87], s[40:41], 0, v[86:87]
	v_lshl_add_u64 v[86:87], v[86:87], 0, s[8:9]
	v_lshl_add_u64 v[90:91], v[86:87], 0, v[72:73]
	ds_read2_b32 v[92:93], v79 offset0:16 offset1:24
	ds_read2_b32 v[86:87], v79 offset0:50 offset1:58
	ds_read2_b32 v[94:95], v79 offset0:84 offset1:92
	ds_read2_b32 v[88:89], v79 offset0:118 offset1:126
	global_store_dwordx4 v[90:91], v[74:77], off nt
	v_add_u32_e32 v90, s52, v81
	v_ashrrev_i32_e32 v91, 31, v90
	v_lshlrev_b64 v[90:91], 13, v[90:91]
	v_lshl_add_u64 v[90:91], s[40:41], 0, v[90:91]
	v_lshl_add_u64 v[90:91], v[90:91], 0, s[8:9]
	s_waitcnt lgkmcnt(3)
	v_mov_b32_e32 v74, v92
	s_waitcnt lgkmcnt(2)
	v_mov_b32_e32 v75, v86
	s_waitcnt lgkmcnt(1)
	v_mov_b32_e32 v76, v94
	s_waitcnt lgkmcnt(0)
	v_mov_b32_e32 v77, v88
	v_lshl_add_u64 v[90:91], v[90:91], 0, v[72:73]
	global_store_dwordx4 v[90:91], v[74:77], off nt
	v_mov_b32_e32 v86, v93
	v_mov_b32_e32 v88, v95
	v_add_u32_e32 v74, s52, v82
	v_ashrrev_i32_e32 v75, 31, v74
	v_lshlrev_b64 v[74:75], 13, v[74:75]
	v_lshl_add_u64 v[74:75], s[40:41], 0, v[74:75]
	v_lshl_add_u64 v[74:75], v[74:75], 0, s[8:9]
	v_lshl_add_u64 v[74:75], v[74:75], 0, v[72:73]
	global_store_dwordx4 v[74:75], v[86:89], off nt
	s_waitcnt lgkmcnt(0)
	s_and_b64 vcc, exec, s[6:7]
	s_mov_b64 s[8:9], -1
	s_cbranch_vccnz .LBB0_2035
	s_add_i32 s25, s25, 2
	s_cmp_lt_u32 s57, 14
	s_cselect_b64 s[6:7], -1, 0
	s_cmp_lt_i32 s25, 0xe000
	s_cselect_b64 s[8:9], -1, 0
	s_and_b64 s[6:7], s[6:7], s[8:9]
	s_xor_b64 s[8:9], s[6:7], -1
	s_and_b64 vcc, exec, s[8:9]
	s_cbranch_vccnz .LBB0_2141
	s_cmpk_gt_i32 s25, 0x1fff
	s_cbranch_scc0 .LBB0_2139
	s_add_i32 s14, s25, 0xe000
	s_and_b32 s15, s14, 0xffff
	s_mul_i32 s15, s15, 0xaaab
	s_lshr_b32 s15, s15, 25
	s_mul_i32 s27, s15, 0x300
	s_sub_i32 s14, s14, s27
	s_lshl_b32 s27, s14, 5
	s_and_b32 s51, s27, 0xffe0
	s_and_b32 s14, s14, 0xffff
	s_add_i32 s27, s51, 0xffffd000
	s_cmpk_lt_u32 s14, 0x180
	s_cselect_b32 s14, s51, s27
	s_cselect_b32 s27, 0, 0x80
	s_lshl_b32 s28, s14, 1
	s_and_b32 s14, s14, 0x60
	s_and_b32 s28, s28, 0xffffff00
	s_or_b32 s14, s14, s27
	s_or_b32 s52, s14, s28
	s_lshl_b32 s36, s15, 6
	s_mov_b64 s[28:29], s[44:45]
	s_mov_b64 s[34:35], s[18:19]
	s_movk_i32 s38, 0x6000
	s_mov_b64 s[40:41], s[48:49]
	s_cbranch_execz .LBB0_2140
	s_branch .LBB0_2141

; #define GAS __attribute__((address_space(1)))
; #define LAS __attribute__((address_space(3)))
; __device__ __forceinline__ unsigned pk2(float lo, float hi) { return pg8::cvt_pk_bf16(lo, hi); }
; #define LDS_WAIT() asm volatile("s_waitcnt lgkmcnt(0)" ::: "memory")
; __device__ __forceinline__ void tr_store(const TrItem& t, const float (&tv)[32], LAS float* scr, int lane) {
;     const float* gp = t.gk ? t.gk + t.k0 + 32 * (lane >> 5) : nullptr; LAS unsigned* T = (LAS unsigned*)scr;
; #pragma unroll
;     for (int j = 0; j < 16; ++j) { float a = tv[2 * j], b = tv[2 * j + 1]; if (gp) { a *= gp[2 * j]; b *= gp[2 * j + 1]; } T[(16 * (lane >> 5) + j) * TR_P + (lane & 31)] = pk2(a, b); }
;     LDS_WAIT(); asm volatile("" ::: "memory");
;     const int c = lane & 7;
; #pragma unroll
;     for (int j = 0; j < 4; ++j) { const int n = (lane >> 3) + 8 * j; const LAS unsigned* s = T + (4 * c) * TR_P + n;
;         v4u o; o.x = s[0 * TR_P]; o.y = s[1 * TR_P]; o.z = s[2 * TR_P]; o.w = s[3 * TR_P];
;         *(GAS v4u*)(t.WT + (size_t)(t.drow + n) * t.K + t.k0 + 8 * c) = o; }
;     LDS_WAIT(); asm volatile("" ::: "memory");
; }
.LBB0_2235:
	s_nop 0
	v_cvt_pk_bf16_f32 v1, v76, v77
	ds_write_b32 v84, v1
	s_waitcnt lgkmcnt(0)
	ds_read2_b32 v[90:91], v79 offset1:8
	ds_read2_b32 v[74:75], v79 offset0:34 offset1:42
	ds_read2_b32 v[92:93], v79 offset0:68 offset1:76
	ds_read2_b32 v[76:77], v79 offset0:102 offset1:110
	v_add_u32_e32 v94, s50, v78
	v_ashrrev_i32_e32 v95, 31, v94
	v_lshlrev_b64 v[94:95], 13, v[94:95]
	v_lshl_add_u64 v[94:95], s[30:31], 0, v[94:95]
	s_lshl_b64 s[6:7], s[24:25], 1
	v_lshl_add_u64 v[94:95], v[94:95], 0, s[6:7]
	v_mov_b32_e32 v73, v3
	s_waitcnt lgkmcnt(3)
	v_mov_b32_e32 v86, v90
	s_waitcnt lgkmcnt(2)
	v_mov_b32_e32 v87, v74
	s_waitcnt lgkmcnt(1)
	v_mov_b32_e32 v88, v92
	s_waitcnt lgkmcnt(0)
	v_mov_b32_e32 v89, v76
	v_lshl_add_u64 v[94:95], v[94:95], 0, v[72:73]
	global_store_dwordx4 v[94:95], v[86:89], off nt
	v_mov_b32_e32 v74, v91
	v_mov_b32_e32 v76, v93
	v_add_u32_e32 v86, s50, v80
	v_ashrrev_i32_e32 v87, 31, v86
	v_lshlrev_b64 v[86:87], 13, v[86:87]
	v_lshl_add_u64 v[86:87], s[30:31], 0, v[86:87]
	v_lshl_add_u64 v[86:87], v[86:87], 0, s[6:7]
	v_lshl_add_u64 v[90:91], v[86:87], 0, v[72:73]
	ds_read2_b32 v[92:93], v79 offset0:16 offset1:24
	ds_read2_b32 v[86:87], v79 offset0:50 offset1:58
	ds_read2_b32 v[94:95], v79 offset0:84 offset1:92
	ds_read2_b32 v[88:89], v79 offset0:118 offset1:126
	global_store_dwordx4 v[90:91], v[74:77], off nt
	v_add_u32_e32 v90, s50, v81
	v_ashrrev_i32_e32 v91, 31, v90
	v_lshlrev_b64 v[90:91], 13, v[90:91]
	v_lshl_add_u64 v[90:91], s[30:31], 0, v[90:91]
	v_lshl_add_u64 v[90:91], v[90:91], 0, s[6:7]
	s_waitcnt lgkmcnt(3)
	v_mov_b32_e32 v74, v92
	s_waitcnt lgkmcnt(2)
	v_mov_b32_e32 v75, v86
	s_waitcnt lgkmcnt(1)
	v_mov_b32_e32 v76, v94
	s_waitcnt lgkmcnt(0)
	v_mov_b32_e32 v77, v88
	v_lshl_add_u64 v[90:91], v[90:91], 0, v[72:73]
	global_store_dwordx4 v[90:91], v[74:77], off nt
	v_mov_b32_e32 v86, v93
	v_mov_b32_e32 v88, v95
	v_add_u32_e32 v74, s50, v82
	v_ashrrev_i32_e32 v75, 31, v74
	v_lshlrev_b64 v[74:75], 13, v[74:75]
	v_lshl_add_u64 v[74:75], s[30:31], 0, v[74:75]
	v_lshl_add_u64 v[74:75], v[74:75], 0, s[6:7]
	v_lshl_add_u64 v[74:75], v[74:75], 0, v[72:73]
	global_store_dwordx4 v[74:75], v[86:89], off nt
	s_waitcnt lgkmcnt(0)
	s_add_i32 s57, s57, 2
	s_and_b64 vcc, exec, s[8:9]
	s_cbranch_vccz .LBB0_2036
	s_branch .LBB0_1960

;     __device__ __forceinline__ void operator()(const f32x4 (&acc)[2][2][4][2], const Unit& u, int wr, int wc, int fr, int fq) const {
;         const int pm = u.pm, row0 = pm * BM + wr * 64 + fr, col0 = u.pn * HALF + wc * 32 + 8 * fq, lane = fq * 16 + fr;
;         const float* rs3 = (const float*)(ws + WS_RS3); bf16_t* ACT = (bf16_t*)(ws + WS_ACT);
;         float *HEADG = (float*)(ws + WS_HEADG), *HEADV = (float*)(ws + WS_HEADV), *TAILG = (float*)(ws + WS_TAILG), *o_fcp = out + O_FCP, *o_fcs = out + O_FCS;
;         f32x4 w0[2], w1[2], w2[2], bb[2];
; #pragma unroll
;         for (int n = 0; n < 2; ++n) { w0[n] = *(const f32x4*)(wconv + col0 + 4 * n); w1[n] = *(const f32x4*)(wconv + DFF + col0 + 4 * n); w2[n] = *(const f32x4*)(wconv + 2 * DFF + col0 + 4 * n); bb[n] = *(const f32x4*)(bconv + col0 + 4 * n); }
;         float sc8[2][4];
; #pragma unroll
;         for (int ai = 0; ai < 2; ++ai)
; #pragma unroll
;             for (int m = 0; m < 4; ++m) sc8[ai][m] = rs3[row0 + ai * HALF + m * 16];
; #pragma unroll
;         for (int ai = 0; ai < 2; ++ai) { f32x4 zprev[2] = {(f32x4){0.f, 0.f, 0.f, 0.f}, (f32x4){0.f, 0.f, 0.f, 0.f}};
; #pragma unroll
;             for (int m = 0; m < 4; ++m) { const int row = row0 + ai * HALF + m * 16; const float s = sc8[ai][m];
;                 f32x4 zc[2], zp[2], vv[2], z1[2], z2[2];
; #pragma unroll
;                 for (int n = 0; n < 2; ++n) { zc[n] = acc[ai][0][m][n] * s; vv[n] = acc[ai][1][m][n] * s; zp[n] = zprev[n]; zprev[n] = zc[n]; }
; #pragma unroll
;                 for (int n = 0; n < 2; ++n)
; #pragma unroll
;                     for (int e = 0; e < 4; ++e) { const float t1 = fr == 15 ? zp[n][e] : zc[n][e], t2 = fr >= 14 ? zp[n][e] : zc[n][e];
;                         z1[n][e] = __builtin_bit_cast(float, __builtin_amdgcn_mov_dpp(__builtin_bit_cast(int, t1), 0x121, 0xf, 0xf, true));
;                         z2[n][e] = __builtin_bit_cast(float, __builtin_amdgcn_mov_dpp(__builtin_bit_cast(int, t2), 0x122, 0xf, 0xf, true)); }
;                 if (pm == 0) {
;                     if (fr < 2) { const float* st = stf + (size_t)(row >> 4) * 2 * DFF + col0;
; #pragma unroll
;                         for (int n = 0; n < 2; ++n) { const f32x4 b0 = *(const f32x4*)(st + 4 * n), b1 = *(const f32x4*)(st + DFF + 4 * n); if (fr == 0) { z1[n] = b1; z2[n] = b0; } else { z2[n] = b1; } } }
.LBB0_2653:
	s_lshl_b32 s69, s18, 8
	s_add_i32 s69, s69, s28
	v_lshl_or_b32 v212, s84, 7, v183
	v_or_b32_e32 v214, s69, v194
	v_ashrrev_i32_e32 v213, 31, v212
	v_ashrrev_i32_e32 v215, 31, v214
	v_lshlrev_b64 v[14:15], 2, v[212:213]
	v_lshl_add_u64 v[10:11], v[214:215], 2, s[52:53]
	v_lshl_add_u64 v[12:13], s[24:25], 0, v[14:15]
	v_lshl_add_u64 v[54:55], s[50:51], 0, v[14:15]
	v_lshl_add_u64 v[70:71], s[26:27], 0, v[14:15]
	v_or_b32_e32 v232, 16, v214
	v_or_b32_e32 v228, 32, v214
	v_or_b32_e32 v224, 48, v214
	global_load_dword v236, v[10:11], off
	v_lshl_add_u64 v[16:17], s[48:49], 0, v[14:15]
	global_load_dwordx4 v[50:53], v[12:13], off offset:16
	global_load_dwordx4 v[66:69], v[12:13], off
	global_load_dwordx4 v[46:49], v[16:17], off offset:16
	global_load_dwordx4 v[62:65], v[16:17], off
	global_load_dwordx4 v[42:45], v[54:55], off offset:16
	global_load_dwordx4 v[58:61], v[54:55], off
	s_nop 0
	global_load_dwordx4 v[54:57], v[70:71], off offset:16
	s_nop 0
	global_load_dwordx4 v[70:73], v[70:71], off
	v_ashrrev_i32_e32 v233, 31, v232
	v_ashrrev_i32_e32 v229, 31, v228
	v_ashrrev_i32_e32 v225, 31, v224
	v_lshl_add_u64 v[12:13], v[232:233], 2, s[52:53]
	v_lshl_add_u64 v[16:17], v[228:229], 2, s[52:53]
	v_lshl_add_u64 v[170:171], v[224:225], 2, s[52:53]
	global_load_dword v222, v[10:11], off offset:512
	global_load_dword v220, v[10:11], off offset:576
	global_load_dword v218, v[10:11], off offset:640
	global_load_dword v234, v[12:13], off
	global_load_dword v230, v[16:17], off
	global_load_dword v226, v[170:171], off
	global_load_dword v208, v[10:11], off offset:704
	s_cmp_lg_u32 s18, 0
	s_cselect_b64 s[90:91], -1, 0
	s_and_b64 vcc, exec, s[90:91]
	s_waitcnt vmcnt(0)
	v_pk_mul_f32 v[176:177], v[8:9], v[236:237] op_sel_hi:[1,0]
	v_pk_mul_f32 v[174:175], v[6:7], v[236:237] op_sel_hi:[1,0]
	v_pk_mul_f32 v[172:173], v[4:5], v[236:237] op_sel_hi:[1,0]
	v_pk_mul_f32 v[170:171], v[2:3], v[236:237] op_sel_hi:[1,0]
	v_cndmask_b32_e64 v2, v174, 0, s[6:7]
	v_cndmask_b32_e64 v3, v174, 0, s[8:9]
	v_cndmask_b32_e64 v4, v175, 0, s[6:7]
	v_cndmask_b32_e64 v5, v175, 0, s[8:9]
	v_cndmask_b32_e64 v6, v176, 0, s[6:7]
	v_cndmask_b32_e64 v7, v176, 0, s[8:9]
	v_cndmask_b32_e64 v8, v177, 0, s[6:7]
	v_cndmask_b32_e64 v9, v177, 0, s[8:9]
	v_cndmask_b32_e64 v10, v170, 0, s[6:7]
	v_cndmask_b32_e64 v11, v170, 0, s[8:9]
	v_cndmask_b32_e64 v12, v171, 0, s[6:7]
	v_cndmask_b32_e64 v13, v171, 0, s[8:9]
	v_cndmask_b32_e64 v16, v172, 0, s[6:7]
	v_cndmask_b32_e64 v17, v172, 0, s[8:9]
	v_cndmask_b32_e64 v192, v173, 0, s[6:7]
	v_cndmask_b32_e64 v209, v173, 0, s[8:9]
	v_mov_b32_dpp v2, v2 row_ror:1 row_mask:0xf bank_mask:0xf bound_ctrl:1
	v_mov_b32_dpp v178, v3 row_ror:2 row_mask:0xf bank_mask:0xf bound_ctrl:1
	v_mov_b32_dpp v3, v4 row_ror:1 row_mask:0xf bank_mask:0xf bound_ctrl:1
	v_mov_b32_dpp v179, v5 row_ror:2 row_mask:0xf bank_mask:0xf bound_ctrl:1
	v_mov_b32_dpp v4, v6 row_ror:1 row_mask:0xf bank_mask:0xf bound_ctrl:1
	v_mov_b32_dpp v180, v7 row_ror:2 row_mask:0xf bank_mask:0xf bound_ctrl:1
	v_mov_b32_dpp v5, v8 row_ror:1 row_mask:0xf bank_mask:0xf bound_ctrl:1
	v_mov_b32_dpp v181, v9 row_ror:2 row_mask:0xf bank_mask:0xf bound_ctrl:1
	v_mov_b32_dpp v6, v10 row_ror:1 row_mask:0xf bank_mask:0xf bound_ctrl:1
	v_mov_b32_dpp v10, v11 row_ror:2 row_mask:0xf bank_mask:0xf bound_ctrl:1
	v_mov_b32_dpp v7, v12 row_ror:1 row_mask:0xf bank_mask:0xf bound_ctrl:1
	v_mov_b32_dpp v11, v13 row_ror:2 row_mask:0xf bank_mask:0xf bound_ctrl:1
	v_mov_b32_dpp v8, v16 row_ror:1 row_mask:0xf bank_mask:0xf bound_ctrl:1
	v_mov_b32_dpp v12, v17 row_ror:2 row_mask:0xf bank_mask:0xf bound_ctrl:1
	v_mov_b32_dpp v9, v192 row_ror:1 row_mask:0xf bank_mask:0xf bound_ctrl:1
	v_mov_b32_dpp v13, v209 row_ror:2 row_mask:0xf bank_mask:0xf bound_ctrl:1
	s_cbranch_vccz .LBB0_2670
	v_and_b32_e32 v16, 0xffffffce, v214
	v_cmp_eq_u32_e32 vcc, s71, v16
	s_mov_b64 s[86:87], 0
	s_mov_b64 s[84:85], 0
	s_and_saveexec_b64 s[88:89], vcc
	s_xor_b64 s[88:89], exec, s[88:89]
	s_cbranch_execz .LBB0_2656
	v_mul_lo_u32 v192, v214, s68
	v_lshl_add_u64 v[16:17], v[192:193], 2, s[20:21]
	s_mov_b32 s58, 0xe3870400
	v_lshl_add_u64 v[210:211], v[212:213], 2, v[16:17]
	s_mov_b32 s59, -1
	v_lshl_add_u64 v[16:17], v[210:211], 0, s[58:59]
	v_add_co_u32_e32 v210, vcc, 0xe3871000, v210
	s_mov_b64 s[84:85], exec
	s_nop 0
	v_addc_co_u32_e32 v211, vcc, -1, v211, vcc
	global_store_dwordx4 v[210:211], v[174:177], off offset:-3072 nt

;     __device__ __forceinline__ void operator()(const f32x4 (&acc)[2][2][4][2], const Unit& u, int wr, int wc, int fr, int fq) const {
;     ...
;                     const int s16 = row & 15;
;                     if (s16 >= 14) { float* dst = o_fcs + (size_t)((row >> 4) * 2 + (s16 - 14)) * DFF + col0; *(f32x4*)dst = zc[0]; *(f32x4*)(dst + 4) = zc[1]; }
;                 } else { const int t = row - G_ROWP; if (t >= G_TP - 2 && t < G_TP) { float* dst = o_fcp + (size_t)(t - (G_TP - 2)) * DFF + col0; *(f32x4*)dst = zc[0]; *(f32x4*)(dst + 4) = zc[1]; } }
.LBB0_2667:
	s_or_b64 exec, exec, s[86:87]
	s_and_saveexec_b64 s[86:87], s[8:9]
	s_cbranch_execz .LBB0_2669
	v_lshl_add_u64 v[16:17], v[210:211], 0, v[198:199]
	s_or_b64 s[84:85], s[84:85], exec
	global_store_dwordx4 v[16:17], v[174:177], off nt

; __device__ __forceinline__ u32x4 pack8(f32x4 a, f32x4 b) { u32x4 w; w.x = cvt_pk_bf16(a[0], a[1]); w.y = cvt_pk_bf16(a[2], a[3]); w.z = cvt_pk_bf16(b[0], b[1]); w.w = cvt_pk_bf16(b[2], b[3]); return w; }
;     __device__ __forceinline__ void operator()(const f32x4 (&acc)[2][2][4][2], const Unit& u, int wr, int wc, int fr, int fq) const {
;     ...
;                     if (s16 >= 14) { float* dst = o_fcs + (size_t)((row >> 4) * 2 + (s16 - 14)) * DFF + col0; *(f32x4*)dst = zc[0]; *(f32x4*)(dst + 4) = zc[1]; }
;                 } else { const int t = row - G_ROWP; if (t >= G_TP - 2 && t < G_TP) { float* dst = o_fcp + (size_t)(t - (G_TP - 2)) * DFF + col0; *(f32x4*)dst = zc[0]; *(f32x4*)(dst + 4) = zc[1]; } }
;                 const bool defer = pm != 0 && m == 0 && fr < 2;
;                 if (!defer) { f32x4 a[2];
; #pragma unroll
;                     for (int n = 0; n < 2; ++n)
;                     { const f32x4 g = bb[n] + w0[n] * z2[n] + w1[n] * z1[n] + w2[n] * zc[n]; a[n] = gelu4(g) * vv[n]; }
;                     *(u32x4*)(ACT + (size_t)row * DFF + col0) = pack8(a[0], a[1]);
;                 } else { const size_t o = ((size_t)((row - G_ROWP) >> 6) * 2 + fr) * DFF + col0;
;                     *(f32x4*)(HEADG + o) = zc[0]; *(f32x4*)(HEADG + o + 4) = zc[1]; *(f32x4*)(HEADV + o) = vv[0]; *(f32x4*)(HEADV + o + 4) = vv[1]; }
.LBB0_2672:
	global_store_dwordx4 v[16:17], v[170:173], off offset:16 nt
.LBB0_2673:
	s_or_b64 exec, exec, s[86:87]
	s_cmp_lg_u32 s18, 0
	s_cselect_b64 s[86:87], -1, 0
	v_mov_b32_e32 v237, v236
	v_mov_b32_e32 v14, v236
	v_mov_b32_e32 v15, v236
	s_and_b64 s[18:19], s[86:87], s[10:11]
	v_lshl_add_u64 v[216:217], v[212:213], 1, s[44:45]
	v_pk_mul_f32 v[168:169], v[168:169], v[14:15]
	v_pk_mul_f32 v[166:167], v[166:167], v[236:237]
	v_pk_mul_f32 v[16:17], v[164:165], v[14:15]
	v_pk_mul_f32 v[14:15], v[162:163], v[236:237]
	s_xor_b64 s[84:85], s[18:19], -1
	s_and_saveexec_b64 s[18:19], s[84:85]
	s_xor_b64 s[18:19], exec, s[18:19]
	s_cbranch_execz .LBB0_2675
	v_pk_fma_f32 v[162:163], v[68:69], v[180:181], v[72:73]
	v_pk_fma_f32 v[164:165], v[66:67], v[178:179], v[70:71]
	v_pk_fma_f32 v[10:11], v[50:51], v[10:11], v[54:55]
	v_pk_fma_f32 v[4:5], v[64:65], v[4:5], v[162:163]
	v_pk_fma_f32 v[2:3], v[62:63], v[2:3], v[164:165]
	v_pk_fma_f32 v[6:7], v[46:47], v[6:7], v[10:11]
	v_pk_fma_f32 v[4:5], v[60:61], v[176:177], v[4:5]
	v_pk_fma_f32 v[2:3], v[58:59], v[174:175], v[2:3]
	v_pk_fma_f32 v[12:13], v[52:53], v[12:13], v[56:57]
	v_pk_fma_f32 v[6:7], v[42:43], v[170:171], v[6:7]
	v_pk_mul_f32 v[162:163], v[4:5], v[4:5]
	v_pk_mul_f32 v[164:165], v[2:3], v[2:3]
	v_mov_b64_e32 v[178:179], s[72:73]
	v_pk_fma_f32 v[8:9], v[48:49], v[8:9], v[12:13]
	v_pk_mul_f32 v[12:13], v[6:7], v[6:7]
	v_pk_fma_f32 v[162:163], v[162:163], s[74:75], v[178:179] op_sel_hi:[1,0,0] neg_lo:[1,0,0] neg_hi:[1,0,0]
	v_pk_fma_f32 v[164:165], v[164:165], s[74:75], v[178:179] op_sel_hi:[1,0,0] neg_lo:[1,0,0] neg_hi:[1,0,0]
	v_pk_fma_f32 v[8:9], v[44:45], v[172:173], v[8:9]
	v_pk_fma_f32 v[12:13], v[12:13], s[74:75], v[178:179] op_sel_hi:[1,0,0] neg_lo:[1,0,0] neg_hi:[1,0,0]
	v_pk_mul_f32 v[162:163], v[4:5], v[162:163]
	v_pk_mul_f32 v[164:165], v[2:3], v[164:165]
	v_pk_mul_f32 v[10:11], v[8:9], v[8:9]
	v_pk_mul_f32 v[12:13], v[6:7], v[12:13]
	v_exp_f32_e32 v164, v164
	v_exp_f32_e32 v165, v165
	v_exp_f32_e32 v162, v162
	v_exp_f32_e32 v163, v163
	v_pk_fma_f32 v[10:11], v[10:11], s[74:75], v[178:179] op_sel_hi:[1,0,0] neg_lo:[1,0,0] neg_hi:[1,0,0]
	v_exp_f32_e32 v12, v12
	v_exp_f32_e32 v13, v13
	v_pk_mul_f32 v[10:11], v[8:9], v[10:11]
	v_pk_add_f32 v[162:163], v[162:163], 1.0 op_sel_hi:[1,0]
	v_exp_f32_e32 v10, v10
	v_exp_f32_e32 v11, v11
	v_pk_add_f32 v[164:165], v[164:165], 1.0 op_sel_hi:[1,0]
	v_pk_add_f32 v[12:13], v[12:13], 1.0 op_sel_hi:[1,0]
	v_rcp_f32_e32 v164, v164
	v_rcp_f32_e32 v165, v165
	v_rcp_f32_e32 v162, v162
	v_rcp_f32_e32 v163, v163
	v_rcp_f32_e32 v12, v12
	v_rcp_f32_e32 v13, v13
	v_pk_add_f32 v[10:11], v[10:11], 1.0 op_sel_hi:[1,0]
	v_pk_mul_f32 v[4:5], v[4:5], v[162:163]
	v_rcp_f32_e32 v10, v10
	v_rcp_f32_e32 v11, v11
	v_pk_mul_f32 v[2:3], v[2:3], v[164:165]
	v_pk_mul_f32 v[6:7], v[6:7], v[12:13]
	v_pk_mul_f32 v[4:5], v[168:169], v[4:5]
	v_pk_mul_f32 v[2:3], v[166:167], v[2:3]
	v_pk_mul_f32 v[6:7], v[14:15], v[6:7]
	v_pk_mul_f32 v[8:9], v[8:9], v[10:11]
	v_cvt_pk_bf16_f32 v2, v2, v3
	v_cvt_pk_bf16_f32 v3, v4, v5
	v_cvt_pk_bf16_f32 v4, v6, v7
	v_mad_i64_i32 v[6:7], s[88:89], v214, s97, v[216:217]
	v_pk_mul_f32 v[8:9], v[16:17], v[8:9]
	s_nop 0
	v_cvt_pk_bf16_f32 v5, v8, v9
	global_store_dwordx4 v[6:7], v[2:5], off nt
.LBB0_2675:
	s_or_saveexec_b64 s[18:19], s[18:19]
	s_add_i32 s58, s69, 0xffffff00
	s_ashr_i32 s88, s58, 6
	s_ashr_i32 s89, s88, 31
	s_lshl_b64 s[88:89], s[88:89], 1
	s_xor_b64 exec, exec, s[18:19]
	s_cbranch_execz .LBB0_2677
	v_add_u32_e32 v2, s88, v194
	v_mad_i64_i32 v[2:3], s[92:93], v2, s68, v[212:213]
	v_lshlrev_b64 v[2:3], 2, v[2:3]
	v_lshl_add_u64 v[4:5], s[64:65], 0, v[2:3]
	v_lshl_add_u64 v[2:3], s[46:47], 0, v[2:3]
	global_store_dwordx4 v[4:5], v[174:177], off nt
	global_store_dwordx4 v[4:5], v[170:173], off offset:16 nt
	global_store_dwordx4 v[2:3], v[166:169], off nt
	global_store_dwordx4 v[2:3], v[14:17], off offset:16 nt

;     __device__ __forceinline__ void operator()(const f32x4 (&acc)[2][2][4][2], const Unit& u, int wr, int wc, int fr, int fq) const {
;     ...
;                     const int s16 = row & 15;
;                     if (s16 >= 14) { float* dst = o_fcs + (size_t)((row >> 4) * 2 + (s16 - 14)) * DFF + col0; *(f32x4*)dst = zc[0]; *(f32x4*)(dst + 4) = zc[1]; }
.LBB0_2688:
	s_or_b64 exec, exec, s[90:91]
	s_and_saveexec_b64 s[90:91], s[8:9]
	s_cbranch_execz .LBB0_2690
	v_ashrrev_i32_e32 v162, 3, v232
	v_and_b32_e32 v162, -6, v162
	v_add_u32_e32 v162, v162, v196
	v_mad_i64_i32 v[162:163], s[92:93], v162, s0, v[210:211]
	global_store_dwordx4 v[162:163], v[158:161], off nt
	global_store_dwordx4 v[162:163], v[14:17], off offset:16 nt

; __device__ __forceinline__ u32x4 pack8(f32x4 a, f32x4 b) { u32x4 w; w.x = cvt_pk_bf16(a[0], a[1]); w.y = cvt_pk_bf16(a[2], a[3]); w.z = cvt_pk_bf16(b[0], b[1]); w.w = cvt_pk_bf16(b[2], b[3]); return w; }
;     __device__ __forceinline__ void operator()(const f32x4 (&acc)[2][2][4][2], const Unit& u, int wr, int wc, int fr, int fq) const {
;     ...
;             for (int m = 0; m < 4; ++m) { const int row = row0 + ai * HALF + m * 16; const float s = sc8[ai][m];
;                 f32x4 zc[2], zp[2], vv[2], z1[2], z2[2];
; #pragma unroll
;                 for (int n = 0; n < 2; ++n) { zc[n] = acc[ai][0][m][n] * s; vv[n] = acc[ai][1][m][n] * s; zp[n] = zprev[n]; zprev[n] = zc[n]; }
; #pragma unroll
;                 for (int n = 0; n < 2; ++n)
; #pragma unroll
;                     for (int e = 0; e < 4; ++e) { const float t1 = fr == 15 ? zp[n][e] : zc[n][e], t2 = fr >= 14 ? zp[n][e] : zc[n][e];
;                         z1[n][e] = __builtin_bit_cast(float, __builtin_amdgcn_mov_dpp(__builtin_bit_cast(int, t1), 0x121, 0xf, 0xf, true));
;                         z2[n][e] = __builtin_bit_cast(float, __builtin_amdgcn_mov_dpp(__builtin_bit_cast(int, t2), 0x122, 0xf, 0xf, true)); }
;                 if (pm == 0) {
;                     if (fr < 2) { const float* st = stf + (size_t)(row >> 4) * 2 * DFF + col0;
; #pragma unroll
;                         for (int n = 0; n < 2; ++n) { const f32x4 b0 = *(const f32x4*)(st + 4 * n), b1 = *(const f32x4*)(st + DFF + 4 * n); if (fr == 0) { z1[n] = b1; z2[n] = b0; } else { z2[n] = b1; } } }
;                     const int s16 = row & 15;
;                     if (s16 >= 14) { float* dst = o_fcs + (size_t)((row >> 4) * 2 + (s16 - 14)) * DFF + col0; *(f32x4*)dst = zc[0]; *(f32x4*)(dst + 4) = zc[1]; }
;                 } else { const int t = row - G_ROWP; if (t >= G_TP - 2 && t < G_TP) { float* dst = o_fcp + (size_t)(t - (G_TP - 2)) * DFF + col0; *(f32x4*)dst = zc[0]; *(f32x4*)(dst + 4) = zc[1]; } }
;                 const bool defer = pm != 0 && m == 0 && fr < 2;
;                 if (!defer) { f32x4 a[2];
; #pragma unroll
;                     for (int n = 0; n < 2; ++n)
;                     { const f32x4 g = bb[n] + w0[n] * z2[n] + w1[n] * z1[n] + w2[n] * zc[n]; a[n] = gelu4(g) * vv[n]; }
;                     *(u32x4*)(ACT + (size_t)row * DFF + col0) = pack8(a[0], a[1]);
.LBB0_2691:
	v_pk_fma_f32 v[4:5], v[68:69], v[4:5], v[72:73]
	v_pk_fma_f32 v[2:3], v[66:67], v[2:3], v[70:71]
	v_pk_fma_f32 v[6:7], v[50:51], v[6:7], v[54:55]
	v_pk_fma_f32 v[4:5], v[64:65], v[156:157], v[4:5]
	v_pk_fma_f32 v[2:3], v[62:63], v[154:155], v[2:3]
	v_pk_fma_f32 v[6:7], v[46:47], v[10:11], v[6:7]
	v_mov_b32_e32 v162, v234
	v_mov_b32_e32 v163, v234
	v_pk_fma_f32 v[4:5], v[60:61], v[160:161], v[4:5]
	v_pk_fma_f32 v[2:3], v[58:59], v[158:159], v[2:3]
	v_pk_fma_f32 v[8:9], v[52:53], v[8:9], v[56:57]
	v_pk_fma_f32 v[6:7], v[42:43], v[14:15], v[6:7]
	v_pk_mul_f32 v[152:153], v[152:153], v[162:163]
	v_pk_mul_f32 v[148:149], v[148:149], v[162:163]
	v_pk_mul_f32 v[154:155], v[4:5], v[4:5]
	v_pk_mul_f32 v[156:157], v[2:3], v[2:3]
	v_mov_b64_e32 v[162:163], s[72:73]
	v_pk_fma_f32 v[8:9], v[48:49], v[12:13], v[8:9]
	v_pk_mul_f32 v[12:13], v[6:7], v[6:7]
	v_pk_fma_f32 v[154:155], v[154:155], s[74:75], v[162:163] op_sel_hi:[1,0,0] neg_lo:[1,0,0] neg_hi:[1,0,0]
	v_pk_fma_f32 v[156:157], v[156:157], s[74:75], v[162:163] op_sel_hi:[1,0,0] neg_lo:[1,0,0] neg_hi:[1,0,0]
	v_pk_fma_f32 v[8:9], v[44:45], v[16:17], v[8:9]
	v_pk_fma_f32 v[12:13], v[12:13], s[74:75], v[162:163] op_sel_hi:[1,0,0] neg_lo:[1,0,0] neg_hi:[1,0,0]
	v_pk_mul_f32 v[154:155], v[4:5], v[154:155]
	v_pk_mul_f32 v[156:157], v[2:3], v[156:157]
	v_pk_mul_f32 v[10:11], v[8:9], v[8:9]
	v_pk_mul_f32 v[12:13], v[6:7], v[12:13]
	v_exp_f32_e32 v156, v156
	v_exp_f32_e32 v157, v157
	v_exp_f32_e32 v154, v154
	v_exp_f32_e32 v155, v155
	v_pk_fma_f32 v[10:11], v[10:11], s[74:75], v[162:163] op_sel_hi:[1,0,0] neg_lo:[1,0,0] neg_hi:[1,0,0]
	v_exp_f32_e32 v12, v12
	v_exp_f32_e32 v13, v13
	v_pk_mul_f32 v[10:11], v[8:9], v[10:11]
	v_pk_add_f32 v[154:155], v[154:155], 1.0 op_sel_hi:[1,0]
	v_exp_f32_e32 v10, v10
	v_exp_f32_e32 v11, v11
	v_pk_add_f32 v[156:157], v[156:157], 1.0 op_sel_hi:[1,0]
	v_pk_add_f32 v[12:13], v[12:13], 1.0 op_sel_hi:[1,0]
	v_rcp_f32_e32 v156, v156
	v_rcp_f32_e32 v157, v157
	v_rcp_f32_e32 v154, v154
	v_rcp_f32_e32 v155, v155
	v_rcp_f32_e32 v12, v12
	v_rcp_f32_e32 v13, v13
	v_pk_add_f32 v[10:11], v[10:11], 1.0 op_sel_hi:[1,0]
	v_mov_b32_e32 v235, v234
	v_rcp_f32_e32 v10, v10
	v_rcp_f32_e32 v11, v11
	v_pk_mul_f32 v[150:151], v[150:151], v[234:235]
	v_pk_mul_f32 v[146:147], v[146:147], v[234:235]
	v_pk_mul_f32 v[4:5], v[4:5], v[154:155]
	v_pk_mul_f32 v[2:3], v[2:3], v[156:157]
	v_pk_mul_f32 v[6:7], v[6:7], v[12:13]
	v_pk_mul_f32 v[4:5], v[152:153], v[4:5]
	v_pk_mul_f32 v[2:3], v[150:151], v[2:3]
	v_pk_mul_f32 v[6:7], v[146:147], v[6:7]
	v_pk_mul_f32 v[8:9], v[8:9], v[10:11]
	v_cvt_pk_bf16_f32 v2, v2, v3
	v_cvt_pk_bf16_f32 v3, v4, v5
	v_cvt_pk_bf16_f32 v4, v6, v7
	v_mad_i64_i32 v[6:7], s[90:91], v232, s97, v[216:217]
	v_pk_mul_f32 v[142:143], v[142:143], v[230:231] op_sel_hi:[1,0]
	v_pk_mul_f32 v[8:9], v[148:149], v[8:9]
	v_pk_mul_f32 v[144:145], v[144:145], v[230:231] op_sel_hi:[1,0]
	v_cvt_pk_bf16_f32 v5, v8, v9
	global_store_dwordx4 v[6:7], v[2:5], off nt
	v_pk_mul_f32 v[10:11], v[138:139], v[230:231] op_sel_hi:[1,0]
	v_pk_mul_f32 v[12:13], v[140:141], v[230:231] op_sel_hi:[1,0]
	v_cndmask_b32_e64 v2, v142, v158, s[6:7]
	v_cndmask_b32_e64 v3, v142, v158, s[8:9]
	v_cndmask_b32_e64 v4, v143, v159, s[8:9]
	v_mov_b32_dpp v138, v2 row_ror:1 row_mask:0xf bank_mask:0xf bound_ctrl:1
	v_mov_b32_dpp v2, v3 row_ror:2 row_mask:0xf bank_mask:0xf bound_ctrl:1
	v_cndmask_b32_e64 v3, v143, v159, s[6:7]
	v_cndmask_b32_e64 v5, v144, v160, s[8:9]
	v_cndmask_b32_e64 v6, v145, v161, s[8:9]
	v_mov_b32_dpp v139, v3 row_ror:1 row_mask:0xf bank_mask:0xf bound_ctrl:1
	v_mov_b32_dpp v3, v4 row_ror:2 row_mask:0xf bank_mask:0xf bound_ctrl:1
	v_cndmask_b32_e64 v4, v144, v160, s[6:7]
	v_cndmask_b32_e64 v7, v10, v14, s[8:9]
	v_cndmask_b32_e64 v8, v11, v15, s[8:9]
	v_mov_b32_dpp v140, v4 row_ror:1 row_mask:0xf bank_mask:0xf bound_ctrl:1
	v_mov_b32_dpp v4, v5 row_ror:2 row_mask:0xf bank_mask:0xf bound_ctrl:1
	v_cndmask_b32_e64 v5, v145, v161, s[6:7]
	v_cndmask_b32_e64 v9, v12, v16, s[8:9]
	v_cndmask_b32_e64 v146, v13, v17, s[8:9]
	v_mov_b32_dpp v141, v5 row_ror:1 row_mask:0xf bank_mask:0xf bound_ctrl:1
	v_mov_b32_dpp v5, v6 row_ror:2 row_mask:0xf bank_mask:0xf bound_ctrl:1
	v_cndmask_b32_e64 v6, v10, v14, s[6:7]
	s_and_b64 vcc, exec, s[18:19]
	s_nop 0
	v_mov_b32_dpp v14, v6 row_ror:1 row_mask:0xf bank_mask:0xf bound_ctrl:1
	v_mov_b32_dpp v6, v7 row_ror:2 row_mask:0xf bank_mask:0xf bound_ctrl:1
	v_cndmask_b32_e64 v7, v11, v15, s[6:7]
	s_nop 1
	v_mov_b32_dpp v15, v7 row_ror:1 row_mask:0xf bank_mask:0xf bound_ctrl:1
	v_mov_b32_dpp v7, v8 row_ror:2 row_mask:0xf bank_mask:0xf bound_ctrl:1
	v_cndmask_b32_e64 v8, v12, v16, s[6:7]
	s_nop 1
	v_mov_b32_dpp v16, v8 row_ror:1 row_mask:0xf bank_mask:0xf bound_ctrl:1
	v_mov_b32_dpp v8, v9 row_ror:2 row_mask:0xf bank_mask:0xf bound_ctrl:1
	v_cndmask_b32_e64 v9, v13, v17, s[6:7]
	s_nop 1
	v_mov_b32_dpp v17, v9 row_ror:1 row_mask:0xf bank_mask:0xf bound_ctrl:1
	v_mov_b32_dpp v9, v146 row_ror:2 row_mask:0xf bank_mask:0xf bound_ctrl:1
	s_cbranch_vccnz .LBB0_2693
	s_cbranch_execz .LBB0_2694
	s_branch .LBB0_2705

;     __device__ __forceinline__ void operator()(const f32x4 (&acc)[2][2][4][2], const Unit& u, int wr, int wc, int fr, int fq) const {
;     ...
;                     const int s16 = row & 15;
;                     if (s16 >= 14) { float* dst = o_fcs + (size_t)((row >> 4) * 2 + (s16 - 14)) * DFF + col0; *(f32x4*)dst = zc[0]; *(f32x4*)(dst + 4) = zc[1]; }
.LBB0_2702:
	s_or_b64 exec, exec, s[90:91]
	s_and_saveexec_b64 s[90:91], s[8:9]
	s_cbranch_execz .LBB0_2704
	v_ashrrev_i32_e32 v146, 3, v228
	v_and_b32_e32 v146, -4, v146
	v_add_u32_e32 v146, v146, v196
	v_mad_i64_i32 v[146:147], s[92:93], v146, s0, v[210:211]
	global_store_dwordx4 v[146:147], v[142:145], off nt
	global_store_dwordx4 v[146:147], v[10:13], off offset:16 nt

; __device__ __forceinline__ u32x4 pack8(f32x4 a, f32x4 b) { u32x4 w; w.x = cvt_pk_bf16(a[0], a[1]); w.y = cvt_pk_bf16(a[2], a[3]); w.z = cvt_pk_bf16(b[0], b[1]); w.w = cvt_pk_bf16(b[2], b[3]); return w; }
;     __device__ __forceinline__ void operator()(const f32x4 (&acc)[2][2][4][2], const Unit& u, int wr, int wc, int fr, int fq) const {
;     ...
;             for (int m = 0; m < 4; ++m) { const int row = row0 + ai * HALF + m * 16; const float s = sc8[ai][m];
;                 f32x4 zc[2], zp[2], vv[2], z1[2], z2[2];
; #pragma unroll
;                 for (int n = 0; n < 2; ++n) { zc[n] = acc[ai][0][m][n] * s; vv[n] = acc[ai][1][m][n] * s; zp[n] = zprev[n]; zprev[n] = zc[n]; }
; #pragma unroll
;                 for (int n = 0; n < 2; ++n)
; #pragma unroll
;                     for (int e = 0; e < 4; ++e) { const float t1 = fr == 15 ? zp[n][e] : zc[n][e], t2 = fr >= 14 ? zp[n][e] : zc[n][e];
;                         z1[n][e] = __builtin_bit_cast(float, __builtin_amdgcn_mov_dpp(__builtin_bit_cast(int, t1), 0x121, 0xf, 0xf, true));
;                         z2[n][e] = __builtin_bit_cast(float, __builtin_amdgcn_mov_dpp(__builtin_bit_cast(int, t2), 0x122, 0xf, 0xf, true)); }
;                 if (pm == 0) {
;                     if (fr < 2) { const float* st = stf + (size_t)(row >> 4) * 2 * DFF + col0;
; #pragma unroll
;                         for (int n = 0; n < 2; ++n) { const f32x4 b0 = *(const f32x4*)(st + 4 * n), b1 = *(const f32x4*)(st + DFF + 4 * n); if (fr == 0) { z1[n] = b1; z2[n] = b0; } else { z2[n] = b1; } } }
;                     const int s16 = row & 15;
;                     if (s16 >= 14) { float* dst = o_fcs + (size_t)((row >> 4) * 2 + (s16 - 14)) * DFF + col0; *(f32x4*)dst = zc[0]; *(f32x4*)(dst + 4) = zc[1]; }
;                 } else { const int t = row - G_ROWP; if (t >= G_TP - 2 && t < G_TP) { float* dst = o_fcp + (size_t)(t - (G_TP - 2)) * DFF + col0; *(f32x4*)dst = zc[0]; *(f32x4*)(dst + 4) = zc[1]; } }
;                 const bool defer = pm != 0 && m == 0 && fr < 2;
;                 if (!defer) { f32x4 a[2];
; #pragma unroll
;                     for (int n = 0; n < 2; ++n)
;                     { const f32x4 g = bb[n] + w0[n] * z2[n] + w1[n] * z1[n] + w2[n] * zc[n]; a[n] = gelu4(g) * vv[n]; }
;                     *(u32x4*)(ACT + (size_t)row * DFF + col0) = pack8(a[0], a[1]);
.LBB0_2705:
	v_pk_fma_f32 v[4:5], v[68:69], v[4:5], v[72:73]
	v_pk_fma_f32 v[2:3], v[66:67], v[2:3], v[70:71]
	v_pk_fma_f32 v[6:7], v[50:51], v[6:7], v[54:55]
	v_pk_fma_f32 v[4:5], v[64:65], v[140:141], v[4:5]
	v_pk_fma_f32 v[2:3], v[62:63], v[138:139], v[2:3]
	v_pk_fma_f32 v[6:7], v[46:47], v[14:15], v[6:7]
	v_mov_b32_e32 v146, v230
	v_mov_b32_e32 v147, v230
	v_pk_fma_f32 v[4:5], v[60:61], v[144:145], v[4:5]
	v_pk_fma_f32 v[2:3], v[58:59], v[142:143], v[2:3]
	v_pk_fma_f32 v[8:9], v[52:53], v[8:9], v[56:57]
	v_pk_fma_f32 v[6:7], v[42:43], v[10:11], v[6:7]
	v_pk_mul_f32 v[136:137], v[136:137], v[146:147]
	v_pk_mul_f32 v[132:133], v[132:133], v[146:147]
	v_pk_mul_f32 v[138:139], v[4:5], v[4:5]
	v_pk_mul_f32 v[140:141], v[2:3], v[2:3]
	v_mov_b64_e32 v[146:147], s[72:73]
	v_pk_fma_f32 v[8:9], v[48:49], v[16:17], v[8:9]
	v_pk_mul_f32 v[16:17], v[6:7], v[6:7]
	v_pk_fma_f32 v[138:139], v[138:139], s[74:75], v[146:147] op_sel_hi:[1,0,0] neg_lo:[1,0,0] neg_hi:[1,0,0]
	v_pk_fma_f32 v[140:141], v[140:141], s[74:75], v[146:147] op_sel_hi:[1,0,0] neg_lo:[1,0,0] neg_hi:[1,0,0]
	v_pk_fma_f32 v[8:9], v[44:45], v[12:13], v[8:9]
	v_pk_fma_f32 v[16:17], v[16:17], s[74:75], v[146:147] op_sel_hi:[1,0,0] neg_lo:[1,0,0] neg_hi:[1,0,0]
	v_pk_mul_f32 v[138:139], v[4:5], v[138:139]
	v_pk_mul_f32 v[140:141], v[2:3], v[140:141]
	v_pk_mul_f32 v[14:15], v[8:9], v[8:9]
	v_pk_mul_f32 v[16:17], v[6:7], v[16:17]
	v_exp_f32_e32 v140, v140
	v_exp_f32_e32 v141, v141
	v_exp_f32_e32 v138, v138
	v_exp_f32_e32 v139, v139
	v_pk_fma_f32 v[14:15], v[14:15], s[74:75], v[146:147] op_sel_hi:[1,0,0] neg_lo:[1,0,0] neg_hi:[1,0,0]
	v_exp_f32_e32 v16, v16
	v_exp_f32_e32 v17, v17
	v_pk_mul_f32 v[14:15], v[8:9], v[14:15]
	v_pk_add_f32 v[138:139], v[138:139], 1.0 op_sel_hi:[1,0]
	v_exp_f32_e32 v14, v14
	v_exp_f32_e32 v15, v15
	v_pk_add_f32 v[140:141], v[140:141], 1.0 op_sel_hi:[1,0]
	v_pk_add_f32 v[16:17], v[16:17], 1.0 op_sel_hi:[1,0]
	v_rcp_f32_e32 v140, v140
	v_rcp_f32_e32 v141, v141
	v_rcp_f32_e32 v138, v138
	v_rcp_f32_e32 v139, v139
	v_rcp_f32_e32 v16, v16
	v_rcp_f32_e32 v17, v17
	v_pk_add_f32 v[14:15], v[14:15], 1.0 op_sel_hi:[1,0]
	v_mov_b32_e32 v231, v230
	v_rcp_f32_e32 v14, v14
	v_rcp_f32_e32 v15, v15
	v_pk_mul_f32 v[134:135], v[134:135], v[230:231]
	v_pk_mul_f32 v[130:131], v[130:131], v[230:231]
	v_pk_mul_f32 v[4:5], v[4:5], v[138:139]
	v_pk_mul_f32 v[2:3], v[2:3], v[140:141]
	v_pk_mul_f32 v[6:7], v[6:7], v[16:17]
	v_pk_mul_f32 v[4:5], v[136:137], v[4:5]
	v_pk_mul_f32 v[2:3], v[134:135], v[2:3]
	v_pk_mul_f32 v[6:7], v[130:131], v[6:7]
	v_pk_mul_f32 v[8:9], v[8:9], v[14:15]
	v_cvt_pk_bf16_f32 v2, v2, v3
	v_cvt_pk_bf16_f32 v3, v4, v5
	v_cvt_pk_bf16_f32 v4, v6, v7
	v_mad_i64_i32 v[6:7], s[90:91], v228, s97, v[216:217]
	v_pk_mul_f32 v[14:15], v[126:127], v[226:227] op_sel_hi:[1,0]
	v_pk_mul_f32 v[8:9], v[132:133], v[8:9]
	v_pk_mul_f32 v[16:17], v[128:129], v[226:227] op_sel_hi:[1,0]
	v_cvt_pk_bf16_f32 v5, v8, v9
	global_store_dwordx4 v[6:7], v[2:5], off nt
	v_pk_mul_f32 v[122:123], v[122:123], v[226:227] op_sel_hi:[1,0]
	v_cndmask_b32_e64 v6, v17, v145, s[8:9]
	v_cndmask_b32_e64 v2, v14, v142, s[6:7]
	v_cndmask_b32_e64 v3, v14, v142, s[8:9]
	v_cndmask_b32_e64 v4, v15, v143, s[8:9]
	v_mov_b32_dpp v126, v2 row_ror:1 row_mask:0xf bank_mask:0xf bound_ctrl:1
	v_mov_b32_dpp v2, v3 row_ror:2 row_mask:0xf bank_mask:0xf bound_ctrl:1
	v_cndmask_b32_e64 v3, v15, v143, s[6:7]
	v_cndmask_b32_e64 v5, v16, v144, s[8:9]
	v_cndmask_b32_e64 v7, v122, v10, s[8:9]
	v_mov_b32_dpp v127, v3 row_ror:1 row_mask:0xf bank_mask:0xf bound_ctrl:1
	v_mov_b32_dpp v3, v4 row_ror:2 row_mask:0xf bank_mask:0xf bound_ctrl:1
	v_cndmask_b32_e64 v4, v16, v144, s[6:7]
	v_pk_mul_f32 v[124:125], v[124:125], v[226:227] op_sel_hi:[1,0]
	v_cndmask_b32_e64 v8, v123, v11, s[8:9]
	v_mov_b32_dpp v128, v4 row_ror:1 row_mask:0xf bank_mask:0xf bound_ctrl:1
	v_mov_b32_dpp v4, v5 row_ror:2 row_mask:0xf bank_mask:0xf bound_ctrl:1
	v_cndmask_b32_e64 v5, v17, v145, s[6:7]
	v_cndmask_b32_e64 v9, v124, v12, s[8:9]
	v_cndmask_b32_e64 v130, v125, v13, s[8:9]
	v_mov_b32_dpp v129, v5 row_ror:1 row_mask:0xf bank_mask:0xf bound_ctrl:1
	v_mov_b32_dpp v5, v6 row_ror:2 row_mask:0xf bank_mask:0xf bound_ctrl:1
	v_cndmask_b32_e64 v6, v122, v10, s[6:7]
	s_and_b64 vcc, exec, s[18:19]
	s_nop 0
	v_mov_b32_dpp v10, v6 row_ror:1 row_mask:0xf bank_mask:0xf bound_ctrl:1
	v_mov_b32_dpp v6, v7 row_ror:2 row_mask:0xf bank_mask:0xf bound_ctrl:1
	v_cndmask_b32_e64 v7, v123, v11, s[6:7]
	s_nop 1
	v_mov_b32_dpp v11, v7 row_ror:1 row_mask:0xf bank_mask:0xf bound_ctrl:1
	v_mov_b32_dpp v7, v8 row_ror:2 row_mask:0xf bank_mask:0xf bound_ctrl:1
	v_cndmask_b32_e64 v8, v124, v12, s[6:7]
	s_nop 1
	v_mov_b32_dpp v12, v8 row_ror:1 row_mask:0xf bank_mask:0xf bound_ctrl:1
	v_mov_b32_dpp v8, v9 row_ror:2 row_mask:0xf bank_mask:0xf bound_ctrl:1
	v_cndmask_b32_e64 v9, v125, v13, s[6:7]
	s_nop 1
	v_mov_b32_dpp v13, v9 row_ror:1 row_mask:0xf bank_mask:0xf bound_ctrl:1
	v_mov_b32_dpp v9, v130 row_ror:2 row_mask:0xf bank_mask:0xf bound_ctrl:1
	s_cbranch_vccnz .LBB0_2707
	s_cbranch_execz .LBB0_2708
	s_branch .LBB0_2719

;     __device__ __forceinline__ void operator()(const f32x4 (&acc)[2][2][4][2], const Unit& u, int wr, int wc, int fr, int fq) const {
;     ...
;                     const int s16 = row & 15;
;                     if (s16 >= 14) { float* dst = o_fcs + (size_t)((row >> 4) * 2 + (s16 - 14)) * DFF + col0; *(f32x4*)dst = zc[0]; *(f32x4*)(dst + 4) = zc[1]; }
.LBB0_2716:
	s_or_b64 exec, exec, s[90:91]
	s_and_saveexec_b64 s[90:91], s[8:9]
	s_cbranch_execz .LBB0_2718
	v_ashrrev_i32_e32 v130, 3, v224
	v_and_b32_e32 v130, -2, v130
	v_add_u32_e32 v130, v130, v196
	v_mad_i64_i32 v[130:131], s[92:93], v130, s0, v[210:211]
	global_store_dwordx4 v[130:131], v[14:17], off nt
	global_store_dwordx4 v[130:131], v[122:125], off offset:16 nt

;     __device__ __forceinline__ void operator()(const f32x4 (&acc)[2][2][4][2], const Unit& u, int wr, int wc, int fr, int fq) const {
;     ...
;         for (int ai = 0; ai < 2; ++ai) { f32x4 zprev[2] = {(f32x4){0.f, 0.f, 0.f, 0.f}, (f32x4){0.f, 0.f, 0.f, 0.f}};
; #pragma unroll
;             for (int m = 0; m < 4; ++m) { const int row = row0 + ai * HALF + m * 16; const float s = sc8[ai][m];
;                 f32x4 zc[2], zp[2], vv[2], z1[2], z2[2];
; #pragma unroll
;                 for (int n = 0; n < 2; ++n) { zc[n] = acc[ai][0][m][n] * s; vv[n] = acc[ai][1][m][n] * s; zp[n] = zprev[n]; zprev[n] = zc[n]; }
; #pragma unroll
;                 for (int n = 0; n < 2; ++n)
; #pragma unroll
;                     for (int e = 0; e < 4; ++e) { const float t1 = fr == 15 ? zp[n][e] : zc[n][e], t2 = fr >= 14 ? zp[n][e] : zc[n][e];
;                         z1[n][e] = __builtin_bit_cast(float, __builtin_amdgcn_mov_dpp(__builtin_bit_cast(int, t1), 0x121, 0xf, 0xf, true));
;                         z2[n][e] = __builtin_bit_cast(float, __builtin_amdgcn_mov_dpp(__builtin_bit_cast(int, t2), 0x122, 0xf, 0xf, true)); }
;                 if (pm == 0) {
;                     if (fr < 2) { const float* st = stf + (size_t)(row >> 4) * 2 * DFF + col0;
; #pragma unroll
;                         for (int n = 0; n < 2; ++n) { const f32x4 b0 = *(const f32x4*)(st + 4 * n), b1 = *(const f32x4*)(st + DFF + 4 * n); if (fr == 0) { z1[n] = b1; z2[n] = b0; } else { z2[n] = b1; } } }
;                     const int s16 = row & 15;
;     ...
;                 const bool defer = pm != 0 && m == 0 && fr < 2;
;                 if (!defer) { f32x4 a[2];
; #pragma unroll
;                     for (int n = 0; n < 2; ++n)
;                     { const f32x4 g = bb[n] + w0[n] * z2[n] + w1[n] * z1[n] + w2[n] * zc[n]; a[n] = gelu4(g) * vv[n]; }
;                     *(u32x4*)(ACT + (size_t)row * DFF + col0) = pack8(a[0], a[1]);
;                 } else { const size_t o = ((size_t)((row - G_ROWP) >> 6) * 2 + fr) * DFF + col0;
;                     *(f32x4*)(HEADG + o) = zc[0]; *(f32x4*)(HEADG + o + 4) = zc[1]; *(f32x4*)(HEADV + o) = vv[0]; *(f32x4*)(HEADV + o + 4) = vv[1]; }
;                 if (pm != 0 && m == 3 && fr >= 14) { const size_t o = ((size_t)((row - G_ROWP) >> 6) * 2 + (fr - 14)) * DFF + col0; *(f32x4*)(TAILG + o) = zc[0]; *(f32x4*)(TAILG + o + 4) = zc[1]; }
.LBB0_2719:
	v_pk_fma_f32 v[4:5], v[68:69], v[4:5], v[72:73]
	v_pk_fma_f32 v[2:3], v[66:67], v[2:3], v[70:71]
	v_pk_fma_f32 v[6:7], v[50:51], v[6:7], v[54:55]
	v_pk_fma_f32 v[4:5], v[64:65], v[128:129], v[4:5]
	v_pk_fma_f32 v[2:3], v[62:63], v[126:127], v[2:3]
	v_pk_fma_f32 v[6:7], v[46:47], v[10:11], v[6:7]
	v_pk_fma_f32 v[4:5], v[60:61], v[16:17], v[4:5]
	v_pk_fma_f32 v[2:3], v[58:59], v[14:15], v[2:3]
	v_pk_fma_f32 v[8:9], v[52:53], v[8:9], v[56:57]
	v_pk_fma_f32 v[6:7], v[42:43], v[122:123], v[6:7]
	v_pk_mul_f32 v[126:127], v[4:5], v[4:5]
	v_pk_mul_f32 v[128:129], v[2:3], v[2:3]
	v_mov_b64_e32 v[132:133], s[72:73]
	v_pk_fma_f32 v[8:9], v[48:49], v[12:13], v[8:9]
	v_pk_mul_f32 v[12:13], v[6:7], v[6:7]
	v_pk_fma_f32 v[126:127], v[126:127], s[74:75], v[132:133] op_sel_hi:[1,0,0] neg_lo:[1,0,0] neg_hi:[1,0,0]
	v_pk_fma_f32 v[128:129], v[128:129], s[74:75], v[132:133] op_sel_hi:[1,0,0] neg_lo:[1,0,0] neg_hi:[1,0,0]
	v_pk_fma_f32 v[8:9], v[44:45], v[124:125], v[8:9]
	v_pk_fma_f32 v[12:13], v[12:13], s[74:75], v[132:133] op_sel_hi:[1,0,0] neg_lo:[1,0,0] neg_hi:[1,0,0]
	v_pk_mul_f32 v[126:127], v[4:5], v[126:127]
	v_pk_mul_f32 v[128:129], v[2:3], v[128:129]
	v_pk_mul_f32 v[10:11], v[8:9], v[8:9]
	v_pk_mul_f32 v[12:13], v[6:7], v[12:13]
	v_exp_f32_e32 v128, v128
	v_exp_f32_e32 v129, v129
	v_exp_f32_e32 v126, v126
	v_exp_f32_e32 v127, v127
	v_pk_fma_f32 v[10:11], v[10:11], s[74:75], v[132:133] op_sel_hi:[1,0,0] neg_lo:[1,0,0] neg_hi:[1,0,0]
	v_exp_f32_e32 v12, v12
	v_exp_f32_e32 v13, v13
	v_pk_mul_f32 v[10:11], v[8:9], v[10:11]
	v_pk_add_f32 v[126:127], v[126:127], 1.0 op_sel_hi:[1,0]
	v_exp_f32_e32 v10, v10
	v_exp_f32_e32 v11, v11
	v_pk_add_f32 v[128:129], v[128:129], 1.0 op_sel_hi:[1,0]
	v_pk_add_f32 v[12:13], v[12:13], 1.0 op_sel_hi:[1,0]
	v_rcp_f32_e32 v128, v128
	v_rcp_f32_e32 v129, v129
	v_rcp_f32_e32 v126, v126
	v_rcp_f32_e32 v127, v127
	v_rcp_f32_e32 v12, v12
	v_rcp_f32_e32 v13, v13
	v_pk_add_f32 v[10:11], v[10:11], 1.0 op_sel_hi:[1,0]
	v_mov_b32_e32 v227, v226
	v_rcp_f32_e32 v10, v10
	v_rcp_f32_e32 v11, v11
	v_mov_b32_e32 v130, v226
	v_mov_b32_e32 v131, v226
	v_pk_mul_f32 v[120:121], v[120:121], v[130:131]
	v_pk_mul_f32 v[118:119], v[118:119], v[226:227]
	v_pk_mul_f32 v[116:117], v[116:117], v[130:131]
	v_pk_mul_f32 v[130:131], v[114:115], v[226:227]
	v_pk_mul_f32 v[4:5], v[4:5], v[126:127]
	v_pk_mul_f32 v[2:3], v[2:3], v[128:129]
	v_pk_mul_f32 v[6:7], v[6:7], v[12:13]
	v_pk_mul_f32 v[4:5], v[120:121], v[4:5]
	v_pk_mul_f32 v[2:3], v[118:119], v[2:3]
	v_pk_mul_f32 v[6:7], v[130:131], v[6:7]
	v_lshl_add_u64 v[114:115], v[212:213], 2, s[54:55]
	v_pk_mul_f32 v[8:9], v[8:9], v[10:11]
	v_cvt_pk_bf16_f32 v2, v2, v3
	v_cvt_pk_bf16_f32 v3, v4, v5
	v_cvt_pk_bf16_f32 v4, v6, v7
	v_mad_i64_i32 v[6:7], s[90:91], v224, s97, v[216:217]
	s_and_b64 s[86:87], s[86:87], s[8:9]
	v_pk_mul_f32 v[8:9], v[116:117], v[8:9]
	s_nop 0
	v_cvt_pk_bf16_f32 v5, v8, v9
	global_store_dwordx4 v[6:7], v[2:5], off nt
	s_and_saveexec_b64 s[90:91], s[86:87]
	s_cbranch_execz .LBB0_2721
	v_lshl_add_u64 v[2:3], s[88:89], 0, v[196:197]
	v_mad_u64_u32 v[4:5], s[88:89], v2, s0, v[114:115]
	v_mad_i32_i24 v5, v3, s0, v5
	global_store_dwordx4 v[4:5], v[14:17], off nt
	global_store_dwordx4 v[4:5], v[122:125], off offset:16 nt
.LBB0_2721:
	s_or_b64 exec, exec, s[90:91]
	v_pk_mul_f32 v[112:113], v[112:113], v[222:223] op_sel_hi:[1,0]
	v_pk_mul_f32 v[110:111], v[110:111], v[222:223] op_sel_hi:[1,0]
	v_pk_mul_f32 v[108:109], v[108:109], v[222:223] op_sel_hi:[1,0]
	v_pk_mul_f32 v[106:107], v[106:107], v[222:223] op_sel_hi:[1,0]
	v_cndmask_b32_e64 v3, v110, 0, s[8:9]
	v_cndmask_b32_e64 v4, v111, 0, s[8:9]
	v_cndmask_b32_e64 v5, v112, 0, s[8:9]
	v_cndmask_b32_e64 v6, v113, 0, s[8:9]
	v_cndmask_b32_e64 v7, v106, 0, s[8:9]
	v_cndmask_b32_e64 v8, v107, 0, s[8:9]
	v_cndmask_b32_e64 v9, v108, 0, s[8:9]
	v_cndmask_b32_e64 v2, v110, 0, s[6:7]
	v_mov_b32_dpp v10, v3 row_ror:2 row_mask:0xf bank_mask:0xf bound_ctrl:1
	v_cndmask_b32_e64 v3, v111, 0, s[6:7]
	v_mov_b32_dpp v11, v4 row_ror:2 row_mask:0xf bank_mask:0xf bound_ctrl:1
	v_cndmask_b32_e64 v4, v112, 0, s[6:7]
	v_mov_b32_dpp v12, v5 row_ror:2 row_mask:0xf bank_mask:0xf bound_ctrl:1
	v_cndmask_b32_e64 v5, v113, 0, s[6:7]
	v_mov_b32_dpp v13, v6 row_ror:2 row_mask:0xf bank_mask:0xf bound_ctrl:1
	v_cndmask_b32_e64 v6, v106, 0, s[6:7]
	v_mov_b32_dpp v14, v7 row_ror:2 row_mask:0xf bank_mask:0xf bound_ctrl:1
	v_cndmask_b32_e64 v7, v107, 0, s[6:7]
	v_mov_b32_dpp v15, v8 row_ror:2 row_mask:0xf bank_mask:0xf bound_ctrl:1
	v_cndmask_b32_e64 v8, v108, 0, s[6:7]
	v_mov_b32_dpp v16, v9 row_ror:2 row_mask:0xf bank_mask:0xf bound_ctrl:1
	v_cndmask_b32_e64 v9, v109, 0, s[6:7]
	v_cndmask_b32_e64 v17, v109, 0, s[8:9]
	v_add_u32_e32 v118, 0x80, v214
	v_mov_b32_dpp v2, v2 row_ror:1 row_mask:0xf bank_mask:0xf bound_ctrl:1
	v_mov_b32_dpp v3, v3 row_ror:1 row_mask:0xf bank_mask:0xf bound_ctrl:1
	v_mov_b32_dpp v4, v4 row_ror:1 row_mask:0xf bank_mask:0xf bound_ctrl:1
	v_mov_b32_dpp v5, v5 row_ror:1 row_mask:0xf bank_mask:0xf bound_ctrl:1
	v_mov_b32_dpp v6, v6 row_ror:1 row_mask:0xf bank_mask:0xf bound_ctrl:1
	v_mov_b32_dpp v7, v7 row_ror:1 row_mask:0xf bank_mask:0xf bound_ctrl:1
	v_mov_b32_dpp v8, v8 row_ror:1 row_mask:0xf bank_mask:0xf bound_ctrl:1
	v_mov_b32_dpp v9, v9 row_ror:1 row_mask:0xf bank_mask:0xf bound_ctrl:1
	s_and_b64 vcc, exec, s[18:19]
	v_mov_b32_dpp v17, v17 row_ror:2 row_mask:0xf bank_mask:0xf bound_ctrl:1
	s_cbranch_vccnz .LBB0_2736
	v_and_b32_e32 v116, 0xffffffce, v118
	v_cmp_eq_u32_e32 vcc, s71, v116
	s_mov_b64 s[90:91], 0
	s_mov_b64 s[88:89], 0
	s_and_saveexec_b64 s[92:93], vcc
	s_cbranch_execz .LBB0_2724
	v_mul_lo_u32 v192, v118, s68
	v_lshl_add_u64 v[116:117], v[192:193], 2, s[20:21]
	s_mov_b32 s58, 0xe3870400
	v_lshl_add_u64 v[120:121], v[212:213], 2, v[116:117]
	s_mov_b32 s59, -1
	v_lshl_add_u64 v[116:117], v[120:121], 0, s[58:59]
	v_add_co_u32_e32 v120, vcc, 0xe3871000, v120
	s_mov_b64 s[88:89], exec
	s_nop 0
	v_addc_co_u32_e32 v121, vcc, -1, v121, vcc
	global_store_dwordx4 v[120:121], v[110:113], off offset:-3072 nt

;     __device__ __forceinline__ void operator()(const f32x4 (&acc)[2][2][4][2], const Unit& u, int wr, int wc, int fr, int fq) const {
;     ...
;                     const int s16 = row & 15;
;                     if (s16 >= 14) { float* dst = o_fcs + (size_t)((row >> 4) * 2 + (s16 - 14)) * DFF + col0; *(f32x4*)dst = zc[0]; *(f32x4*)(dst + 4) = zc[1]; }
;                 } else { const int t = row - G_ROWP; if (t >= G_TP - 2 && t < G_TP) { float* dst = o_fcp + (size_t)(t - (G_TP - 2)) * DFF + col0; *(f32x4*)dst = zc[0]; *(f32x4*)(dst + 4) = zc[1]; } }
.LBB0_2733:
	s_or_b64 exec, exec, s[90:91]
	s_and_saveexec_b64 s[90:91], s[8:9]
	s_cbranch_execz .LBB0_2735
	v_ashrrev_i32_e32 v116, 3, v118
	v_and_b32_e32 v116, -8, v116
	v_add_u32_e32 v116, v116, v196
	v_mad_i64_i32 v[116:117], s[92:93], v116, s0, v[210:211]
	s_or_b64 s[88:89], s[88:89], exec
	global_store_dwordx4 v[116:117], v[110:113], off nt

; __device__ __forceinline__ u32x4 pack8(f32x4 a, f32x4 b) { u32x4 w; w.x = cvt_pk_bf16(a[0], a[1]); w.y = cvt_pk_bf16(a[2], a[3]); w.z = cvt_pk_bf16(b[0], b[1]); w.w = cvt_pk_bf16(b[2], b[3]); return w; }
;     __device__ __forceinline__ void operator()(const f32x4 (&acc)[2][2][4][2], const Unit& u, int wr, int wc, int fr, int fq) const {
;     ...
;                     if (s16 >= 14) { float* dst = o_fcs + (size_t)((row >> 4) * 2 + (s16 - 14)) * DFF + col0; *(f32x4*)dst = zc[0]; *(f32x4*)(dst + 4) = zc[1]; }
;                 } else { const int t = row - G_ROWP; if (t >= G_TP - 2 && t < G_TP) { float* dst = o_fcp + (size_t)(t - (G_TP - 2)) * DFF + col0; *(f32x4*)dst = zc[0]; *(f32x4*)(dst + 4) = zc[1]; } }
;                 const bool defer = pm != 0 && m == 0 && fr < 2;
;                 if (!defer) { f32x4 a[2];
; #pragma unroll
;                     for (int n = 0; n < 2; ++n)
;                     { const f32x4 g = bb[n] + w0[n] * z2[n] + w1[n] * z1[n] + w2[n] * zc[n]; a[n] = gelu4(g) * vv[n]; }
;                     *(u32x4*)(ACT + (size_t)row * DFF + col0) = pack8(a[0], a[1]);
;                 } else { const size_t o = ((size_t)((row - G_ROWP) >> 6) * 2 + fr) * DFF + col0;
;                     *(f32x4*)(HEADG + o) = zc[0]; *(f32x4*)(HEADG + o + 4) = zc[1]; *(f32x4*)(HEADV + o) = vv[0]; *(f32x4*)(HEADV + o + 4) = vv[1]; }
.LBB0_2738:
	global_store_dwordx4 v[116:117], v[106:109], off offset:16 nt
.LBB0_2739:
	s_or_b64 exec, exec, s[90:91]
	v_mov_b32_e32 v223, v222
	v_mov_b32_e32 v116, v222
	v_mov_b32_e32 v117, v222
	v_pk_mul_f32 v[104:105], v[104:105], v[116:117]
	v_pk_mul_f32 v[102:103], v[102:103], v[222:223]
	v_pk_mul_f32 v[100:101], v[100:101], v[116:117]
	v_pk_mul_f32 v[98:99], v[98:99], v[222:223]
	s_and_saveexec_b64 s[88:89], s[84:85]
	s_xor_b64 s[84:85], exec, s[88:89]
	s_cbranch_execz .LBB0_2741
	v_pk_fma_f32 v[10:11], v[66:67], v[10:11], v[70:71]
	v_pk_fma_f32 v[12:13], v[68:69], v[12:13], v[72:73]
	v_pk_fma_f32 v[2:3], v[62:63], v[2:3], v[10:11]
	v_pk_fma_f32 v[4:5], v[64:65], v[4:5], v[12:13]
	v_pk_fma_f32 v[2:3], v[58:59], v[110:111], v[2:3]
	v_mov_b64_e32 v[116:117], s[72:73]
	v_pk_mul_f32 v[12:13], v[2:3], v[2:3]
	v_pk_fma_f32 v[4:5], v[60:61], v[112:113], v[4:5]
	v_pk_fma_f32 v[12:13], v[12:13], s[74:75], v[116:117] op_sel_hi:[1,0,0] neg_lo:[1,0,0] neg_hi:[1,0,0]
	v_pk_mul_f32 v[10:11], v[4:5], v[4:5]
	v_pk_mul_f32 v[12:13], v[2:3], v[12:13]
	v_pk_fma_f32 v[10:11], v[10:11], s[74:75], v[116:117] op_sel_hi:[1,0,0] neg_lo:[1,0,0] neg_hi:[1,0,0]
	v_exp_f32_e32 v12, v12
	v_exp_f32_e32 v13, v13
	v_pk_mul_f32 v[10:11], v[4:5], v[10:11]
	v_pk_add_f32 v[12:13], v[12:13], 1.0 op_sel_hi:[1,0]
	v_exp_f32_e32 v10, v10
	v_exp_f32_e32 v11, v11
	v_rcp_f32_e32 v12, v12
	v_rcp_f32_e32 v13, v13
	v_pk_add_f32 v[10:11], v[10:11], 1.0 op_sel_hi:[1,0]
	s_nop 0
	v_rcp_f32_e32 v10, v10
	v_rcp_f32_e32 v11, v11
	v_pk_mul_f32 v[2:3], v[2:3], v[12:13]
	v_pk_fma_f32 v[12:13], v[50:51], v[14:15], v[54:55]
	v_pk_mul_f32 v[2:3], v[102:103], v[2:3]
	v_pk_fma_f32 v[6:7], v[46:47], v[6:7], v[12:13]
	v_pk_mul_f32 v[4:5], v[4:5], v[10:11]
	v_pk_fma_f32 v[10:11], v[52:53], v[16:17], v[56:57]
	v_pk_fma_f32 v[6:7], v[42:43], v[106:107], v[6:7]
	v_pk_fma_f32 v[8:9], v[48:49], v[8:9], v[10:11]
	v_pk_mul_f32 v[12:13], v[6:7], v[6:7]
	v_pk_fma_f32 v[8:9], v[44:45], v[108:109], v[8:9]
	v_pk_fma_f32 v[12:13], v[12:13], s[74:75], v[116:117] op_sel_hi:[1,0,0] neg_lo:[1,0,0] neg_hi:[1,0,0]
	v_pk_mul_f32 v[10:11], v[8:9], v[8:9]
	v_pk_mul_f32 v[12:13], v[6:7], v[12:13]
	v_pk_fma_f32 v[10:11], v[10:11], s[74:75], v[116:117] op_sel_hi:[1,0,0] neg_lo:[1,0,0] neg_hi:[1,0,0]
	v_exp_f32_e32 v12, v12
	v_exp_f32_e32 v13, v13
	v_pk_mul_f32 v[10:11], v[8:9], v[10:11]
	v_pk_mul_f32 v[4:5], v[104:105], v[4:5]
	v_exp_f32_e32 v10, v10
	v_exp_f32_e32 v11, v11
	v_pk_add_f32 v[12:13], v[12:13], 1.0 op_sel_hi:[1,0]
	v_cvt_pk_bf16_f32 v2, v2, v3
	v_cvt_pk_bf16_f32 v3, v4, v5
	v_pk_add_f32 v[10:11], v[10:11], 1.0 op_sel_hi:[1,0]
	v_rcp_f32_e32 v12, v12
	v_rcp_f32_e32 v13, v13
	v_rcp_f32_e32 v10, v10
	v_rcp_f32_e32 v11, v11
	v_pk_mul_f32 v[6:7], v[6:7], v[12:13]
	s_nop 0
	v_pk_mul_f32 v[6:7], v[98:99], v[6:7]
	v_pk_mul_f32 v[8:9], v[8:9], v[10:11]
	v_cvt_pk_bf16_f32 v4, v6, v7
	v_mad_i64_i32 v[6:7], s[88:89], v118, s97, v[216:217]
	v_pk_mul_f32 v[8:9], v[100:101], v[8:9]
	s_nop 0
	v_cvt_pk_bf16_f32 v5, v8, v9
	global_store_dwordx4 v[6:7], v[2:5], off nt
.LBB0_2741:
	s_or_saveexec_b64 s[88:89], s[84:85]
	s_addk_i32 s69, 0xff80
	s_ashr_i32 s84, s69, 6
	s_ashr_i32 s85, s84, 31
	s_lshl_b64 s[84:85], s[84:85], 1
	s_xor_b64 exec, exec, s[88:89]
	s_cbranch_execz .LBB0_2743
	v_add_u32_e32 v2, s84, v194
	v_mad_i64_i32 v[2:3], s[90:91], v2, s68, v[212:213]
	v_lshlrev_b64 v[2:3], 2, v[2:3]
	v_lshl_add_u64 v[4:5], s[64:65], 0, v[2:3]
	v_lshl_add_u64 v[2:3], s[46:47], 0, v[2:3]
	global_store_dwordx4 v[4:5], v[110:113], off nt
	global_store_dwordx4 v[4:5], v[106:109], off offset:16 nt
	global_store_dwordx4 v[2:3], v[102:105], off nt
	global_store_dwordx4 v[2:3], v[98:101], off offset:16 nt

;     __device__ __forceinline__ void operator()(const f32x4 (&acc)[2][2][4][2], const Unit& u, int wr, int wc, int fr, int fq) const {
;     ...
;                     const int s16 = row & 15;
;                     if (s16 >= 14) { float* dst = o_fcs + (size_t)((row >> 4) * 2 + (s16 - 14)) * DFF + col0; *(f32x4*)dst = zc[0]; *(f32x4*)(dst + 4) = zc[1]; }
.LBB0_2754:
	s_or_b64 exec, exec, s[88:89]
	s_and_saveexec_b64 s[88:89], s[8:9]
	s_cbranch_execz .LBB0_2756
	v_ashrrev_i32_e32 v98, 3, v100
	v_and_b32_e32 v98, -6, v98
	v_add_u32_e32 v98, v98, v196
	v_mad_i64_i32 v[98:99], s[90:91], v98, s0, v[210:211]
	global_store_dwordx4 v[98:99], v[94:97], off nt
	global_store_dwordx4 v[98:99], v[14:17], off offset:16 nt

; __device__ __forceinline__ u32x4 pack8(f32x4 a, f32x4 b) { u32x4 w; w.x = cvt_pk_bf16(a[0], a[1]); w.y = cvt_pk_bf16(a[2], a[3]); w.z = cvt_pk_bf16(b[0], b[1]); w.w = cvt_pk_bf16(b[2], b[3]); return w; }
;     __device__ __forceinline__ void operator()(const f32x4 (&acc)[2][2][4][2], const Unit& u, int wr, int wc, int fr, int fq) const {
;     ...
;             for (int m = 0; m < 4; ++m) { const int row = row0 + ai * HALF + m * 16; const float s = sc8[ai][m];
;                 f32x4 zc[2], zp[2], vv[2], z1[2], z2[2];
; #pragma unroll
;                 for (int n = 0; n < 2; ++n) { zc[n] = acc[ai][0][m][n] * s; vv[n] = acc[ai][1][m][n] * s; zp[n] = zprev[n]; zprev[n] = zc[n]; }
; #pragma unroll
;                 for (int n = 0; n < 2; ++n)
; #pragma unroll
;                     for (int e = 0; e < 4; ++e) { const float t1 = fr == 15 ? zp[n][e] : zc[n][e], t2 = fr >= 14 ? zp[n][e] : zc[n][e];
;                         z1[n][e] = __builtin_bit_cast(float, __builtin_amdgcn_mov_dpp(__builtin_bit_cast(int, t1), 0x121, 0xf, 0xf, true));
;                         z2[n][e] = __builtin_bit_cast(float, __builtin_amdgcn_mov_dpp(__builtin_bit_cast(int, t2), 0x122, 0xf, 0xf, true)); }
;                 if (pm == 0) {
;                     if (fr < 2) { const float* st = stf + (size_t)(row >> 4) * 2 * DFF + col0;
; #pragma unroll
;                         for (int n = 0; n < 2; ++n) { const f32x4 b0 = *(const f32x4*)(st + 4 * n), b1 = *(const f32x4*)(st + DFF + 4 * n); if (fr == 0) { z1[n] = b1; z2[n] = b0; } else { z2[n] = b1; } } }
;                     const int s16 = row & 15;
;                     if (s16 >= 14) { float* dst = o_fcs + (size_t)((row >> 4) * 2 + (s16 - 14)) * DFF + col0; *(f32x4*)dst = zc[0]; *(f32x4*)(dst + 4) = zc[1]; }
;                 } else { const int t = row - G_ROWP; if (t >= G_TP - 2 && t < G_TP) { float* dst = o_fcp + (size_t)(t - (G_TP - 2)) * DFF + col0; *(f32x4*)dst = zc[0]; *(f32x4*)(dst + 4) = zc[1]; } }
;                 const bool defer = pm != 0 && m == 0 && fr < 2;
;                 if (!defer) { f32x4 a[2];
; #pragma unroll
;                     for (int n = 0; n < 2; ++n)
;                     { const f32x4 g = bb[n] + w0[n] * z2[n] + w1[n] * z1[n] + w2[n] * zc[n]; a[n] = gelu4(g) * vv[n]; }
;                     *(u32x4*)(ACT + (size_t)row * DFF + col0) = pack8(a[0], a[1]);
.LBB0_2757:
	v_pk_fma_f32 v[4:5], v[68:69], v[4:5], v[72:73]
	v_pk_fma_f32 v[2:3], v[66:67], v[2:3], v[70:71]
	v_pk_fma_f32 v[6:7], v[50:51], v[6:7], v[54:55]
	v_pk_fma_f32 v[4:5], v[64:65], v[92:93], v[4:5]
	v_pk_fma_f32 v[2:3], v[62:63], v[90:91], v[2:3]
	v_pk_fma_f32 v[6:7], v[46:47], v[10:11], v[6:7]
	v_mov_b32_e32 v98, v220
	v_mov_b32_e32 v99, v220
	v_pk_fma_f32 v[4:5], v[60:61], v[96:97], v[4:5]
	v_pk_fma_f32 v[2:3], v[58:59], v[94:95], v[2:3]
	v_pk_fma_f32 v[8:9], v[52:53], v[8:9], v[56:57]
	v_pk_fma_f32 v[6:7], v[42:43], v[14:15], v[6:7]
	v_pk_mul_f32 v[88:89], v[88:89], v[98:99]
	v_pk_mul_f32 v[84:85], v[84:85], v[98:99]
	v_pk_mul_f32 v[90:91], v[4:5], v[4:5]
	v_pk_mul_f32 v[92:93], v[2:3], v[2:3]
	v_mov_b64_e32 v[98:99], s[72:73]
	v_pk_fma_f32 v[8:9], v[48:49], v[12:13], v[8:9]
	v_pk_mul_f32 v[12:13], v[6:7], v[6:7]
	v_pk_fma_f32 v[90:91], v[90:91], s[74:75], v[98:99] op_sel_hi:[1,0,0] neg_lo:[1,0,0] neg_hi:[1,0,0]
	v_pk_fma_f32 v[92:93], v[92:93], s[74:75], v[98:99] op_sel_hi:[1,0,0] neg_lo:[1,0,0] neg_hi:[1,0,0]
	v_pk_fma_f32 v[8:9], v[44:45], v[16:17], v[8:9]
	v_pk_fma_f32 v[12:13], v[12:13], s[74:75], v[98:99] op_sel_hi:[1,0,0] neg_lo:[1,0,0] neg_hi:[1,0,0]
	v_pk_mul_f32 v[90:91], v[4:5], v[90:91]
	v_pk_mul_f32 v[92:93], v[2:3], v[92:93]
	v_pk_mul_f32 v[10:11], v[8:9], v[8:9]
	v_pk_mul_f32 v[12:13], v[6:7], v[12:13]
	v_exp_f32_e32 v92, v92
	v_exp_f32_e32 v93, v93
	v_exp_f32_e32 v90, v90
	v_exp_f32_e32 v91, v91
	v_pk_fma_f32 v[10:11], v[10:11], s[74:75], v[98:99] op_sel_hi:[1,0,0] neg_lo:[1,0,0] neg_hi:[1,0,0]
	v_exp_f32_e32 v12, v12
	v_exp_f32_e32 v13, v13
	v_pk_mul_f32 v[10:11], v[8:9], v[10:11]
	v_pk_add_f32 v[90:91], v[90:91], 1.0 op_sel_hi:[1,0]
	v_exp_f32_e32 v10, v10
	v_exp_f32_e32 v11, v11
	v_pk_add_f32 v[92:93], v[92:93], 1.0 op_sel_hi:[1,0]
	v_pk_add_f32 v[12:13], v[12:13], 1.0 op_sel_hi:[1,0]
	v_rcp_f32_e32 v92, v92
	v_rcp_f32_e32 v93, v93
	v_rcp_f32_e32 v90, v90
	v_rcp_f32_e32 v91, v91
	v_rcp_f32_e32 v12, v12
	v_rcp_f32_e32 v13, v13
	v_pk_add_f32 v[10:11], v[10:11], 1.0 op_sel_hi:[1,0]
	v_mov_b32_e32 v221, v220
	v_rcp_f32_e32 v10, v10
	v_rcp_f32_e32 v11, v11
	v_pk_mul_f32 v[86:87], v[86:87], v[220:221]
	v_pk_mul_f32 v[82:83], v[82:83], v[220:221]
	v_pk_mul_f32 v[4:5], v[4:5], v[90:91]
	v_pk_mul_f32 v[2:3], v[2:3], v[92:93]
	v_pk_mul_f32 v[6:7], v[6:7], v[12:13]
	v_pk_mul_f32 v[4:5], v[88:89], v[4:5]
	v_pk_mul_f32 v[2:3], v[86:87], v[2:3]
	v_pk_mul_f32 v[6:7], v[82:83], v[6:7]
	v_pk_mul_f32 v[8:9], v[8:9], v[10:11]
	v_cvt_pk_bf16_f32 v2, v2, v3
	v_cvt_pk_bf16_f32 v3, v4, v5
	v_cvt_pk_bf16_f32 v4, v6, v7
	v_mad_i64_i32 v[6:7], s[88:89], v100, s97, v[216:217]
	v_pk_mul_f32 v[78:79], v[78:79], v[218:219] op_sel_hi:[1,0]
	v_pk_mul_f32 v[8:9], v[84:85], v[8:9]
	v_pk_mul_f32 v[80:81], v[80:81], v[218:219] op_sel_hi:[1,0]
	v_cvt_pk_bf16_f32 v5, v8, v9
	global_store_dwordx4 v[6:7], v[2:5], off nt
	v_pk_mul_f32 v[10:11], v[74:75], v[218:219] op_sel_hi:[1,0]
	v_pk_mul_f32 v[12:13], v[76:77], v[218:219] op_sel_hi:[1,0]
	v_cndmask_b32_e64 v2, v78, v94, s[6:7]
	v_cndmask_b32_e64 v3, v78, v94, s[8:9]
	v_cndmask_b32_e64 v4, v79, v95, s[8:9]
	v_mov_b32_dpp v74, v2 row_ror:1 row_mask:0xf bank_mask:0xf bound_ctrl:1
	v_mov_b32_dpp v2, v3 row_ror:2 row_mask:0xf bank_mask:0xf bound_ctrl:1
	v_cndmask_b32_e64 v3, v79, v95, s[6:7]
	v_cndmask_b32_e64 v5, v80, v96, s[8:9]
	v_cndmask_b32_e64 v6, v81, v97, s[8:9]
	v_mov_b32_dpp v75, v3 row_ror:1 row_mask:0xf bank_mask:0xf bound_ctrl:1
	v_mov_b32_dpp v3, v4 row_ror:2 row_mask:0xf bank_mask:0xf bound_ctrl:1
	v_cndmask_b32_e64 v4, v80, v96, s[6:7]
	v_cndmask_b32_e64 v7, v10, v14, s[8:9]
	v_cndmask_b32_e64 v8, v11, v15, s[8:9]
	v_mov_b32_dpp v76, v4 row_ror:1 row_mask:0xf bank_mask:0xf bound_ctrl:1
	v_mov_b32_dpp v4, v5 row_ror:2 row_mask:0xf bank_mask:0xf bound_ctrl:1
	v_cndmask_b32_e64 v5, v81, v97, s[6:7]
	v_cndmask_b32_e64 v9, v12, v16, s[8:9]
	v_cndmask_b32_e64 v82, v13, v17, s[8:9]
	v_mov_b32_dpp v77, v5 row_ror:1 row_mask:0xf bank_mask:0xf bound_ctrl:1
	v_mov_b32_dpp v5, v6 row_ror:2 row_mask:0xf bank_mask:0xf bound_ctrl:1
	v_cndmask_b32_e64 v6, v10, v14, s[6:7]
	s_and_b64 vcc, exec, s[18:19]
	s_nop 0
	v_mov_b32_dpp v14, v6 row_ror:1 row_mask:0xf bank_mask:0xf bound_ctrl:1
	v_mov_b32_dpp v6, v7 row_ror:2 row_mask:0xf bank_mask:0xf bound_ctrl:1
	v_cndmask_b32_e64 v7, v11, v15, s[6:7]
	s_nop 1
	v_mov_b32_dpp v15, v7 row_ror:1 row_mask:0xf bank_mask:0xf bound_ctrl:1
	v_mov_b32_dpp v7, v8 row_ror:2 row_mask:0xf bank_mask:0xf bound_ctrl:1
	v_cndmask_b32_e64 v8, v12, v16, s[6:7]
	s_nop 1
	v_mov_b32_dpp v16, v8 row_ror:1 row_mask:0xf bank_mask:0xf bound_ctrl:1
	v_mov_b32_dpp v8, v9 row_ror:2 row_mask:0xf bank_mask:0xf bound_ctrl:1
	v_cndmask_b32_e64 v9, v13, v17, s[6:7]
	s_nop 1
	v_mov_b32_dpp v17, v9 row_ror:1 row_mask:0xf bank_mask:0xf bound_ctrl:1
	v_mov_b32_dpp v9, v82 row_ror:2 row_mask:0xf bank_mask:0xf bound_ctrl:1
	s_cbranch_vccnz .LBB0_2759
	v_add_u32_e32 v84, 0xa0, v214
	s_cbranch_execz .LBB0_2760
	s_branch .LBB0_2771

;     __device__ __forceinline__ void operator()(const f32x4 (&acc)[2][2][4][2], const Unit& u, int wr, int wc, int fr, int fq) const {
;     ...
;                     const int s16 = row & 15;
;                     if (s16 >= 14) { float* dst = o_fcs + (size_t)((row >> 4) * 2 + (s16 - 14)) * DFF + col0; *(f32x4*)dst = zc[0]; *(f32x4*)(dst + 4) = zc[1]; }
.LBB0_2768:
	s_or_b64 exec, exec, s[88:89]
	s_and_saveexec_b64 s[88:89], s[8:9]
	s_cbranch_execz .LBB0_2770
	v_ashrrev_i32_e32 v82, 3, v84
	v_and_b32_e32 v82, -4, v82
	v_add_u32_e32 v82, v82, v196
	v_mad_i64_i32 v[82:83], s[90:91], v82, s0, v[210:211]
	global_store_dwordx4 v[82:83], v[78:81], off nt
	global_store_dwordx4 v[82:83], v[10:13], off offset:16 nt

; __device__ __forceinline__ u32x4 pack8(f32x4 a, f32x4 b) { u32x4 w; w.x = cvt_pk_bf16(a[0], a[1]); w.y = cvt_pk_bf16(a[2], a[3]); w.z = cvt_pk_bf16(b[0], b[1]); w.w = cvt_pk_bf16(b[2], b[3]); return w; }
;     __device__ __forceinline__ void operator()(const f32x4 (&acc)[2][2][4][2], const Unit& u, int wr, int wc, int fr, int fq) const {
;     ...
;             for (int m = 0; m < 4; ++m) { const int row = row0 + ai * HALF + m * 16; const float s = sc8[ai][m];
;                 f32x4 zc[2], zp[2], vv[2], z1[2], z2[2];
; #pragma unroll
;                 for (int n = 0; n < 2; ++n) { zc[n] = acc[ai][0][m][n] * s; vv[n] = acc[ai][1][m][n] * s; zp[n] = zprev[n]; zprev[n] = zc[n]; }
; #pragma unroll
;                 for (int n = 0; n < 2; ++n)
; #pragma unroll
;                     for (int e = 0; e < 4; ++e) { const float t1 = fr == 15 ? zp[n][e] : zc[n][e], t2 = fr >= 14 ? zp[n][e] : zc[n][e];
;                         z1[n][e] = __builtin_bit_cast(float, __builtin_amdgcn_mov_dpp(__builtin_bit_cast(int, t1), 0x121, 0xf, 0xf, true));
;                         z2[n][e] = __builtin_bit_cast(float, __builtin_amdgcn_mov_dpp(__builtin_bit_cast(int, t2), 0x122, 0xf, 0xf, true)); }
;                 if (pm == 0) {
;                     if (fr < 2) { const float* st = stf + (size_t)(row >> 4) * 2 * DFF + col0;
; #pragma unroll
;                         for (int n = 0; n < 2; ++n) { const f32x4 b0 = *(const f32x4*)(st + 4 * n), b1 = *(const f32x4*)(st + DFF + 4 * n); if (fr == 0) { z1[n] = b1; z2[n] = b0; } else { z2[n] = b1; } } }
;                     const int s16 = row & 15;
;                     if (s16 >= 14) { float* dst = o_fcs + (size_t)((row >> 4) * 2 + (s16 - 14)) * DFF + col0; *(f32x4*)dst = zc[0]; *(f32x4*)(dst + 4) = zc[1]; }
;                 } else { const int t = row - G_ROWP; if (t >= G_TP - 2 && t < G_TP) { float* dst = o_fcp + (size_t)(t - (G_TP - 2)) * DFF + col0; *(f32x4*)dst = zc[0]; *(f32x4*)(dst + 4) = zc[1]; } }
;                 const bool defer = pm != 0 && m == 0 && fr < 2;
;                 if (!defer) { f32x4 a[2];
; #pragma unroll
;                     for (int n = 0; n < 2; ++n)
;                     { const f32x4 g = bb[n] + w0[n] * z2[n] + w1[n] * z1[n] + w2[n] * zc[n]; a[n] = gelu4(g) * vv[n]; }
;                     *(u32x4*)(ACT + (size_t)row * DFF + col0) = pack8(a[0], a[1]);
.LBB0_2771:
	v_pk_fma_f32 v[4:5], v[68:69], v[4:5], v[72:73]
	v_pk_fma_f32 v[2:3], v[66:67], v[2:3], v[70:71]
	v_pk_fma_f32 v[6:7], v[50:51], v[6:7], v[54:55]
	v_pk_fma_f32 v[4:5], v[64:65], v[76:77], v[4:5]
	v_pk_fma_f32 v[2:3], v[62:63], v[74:75], v[2:3]
	v_pk_fma_f32 v[6:7], v[46:47], v[14:15], v[6:7]
	v_mov_b32_e32 v82, v218
	v_mov_b32_e32 v83, v218
	v_pk_fma_f32 v[4:5], v[60:61], v[80:81], v[4:5]
	v_pk_fma_f32 v[2:3], v[58:59], v[78:79], v[2:3]
	v_pk_fma_f32 v[8:9], v[52:53], v[8:9], v[56:57]
	v_pk_fma_f32 v[6:7], v[42:43], v[10:11], v[6:7]
	v_pk_mul_f32 v[40:41], v[40:41], v[82:83]
	v_pk_mul_f32 v[36:37], v[36:37], v[82:83]
	v_pk_mul_f32 v[74:75], v[4:5], v[4:5]
	v_pk_mul_f32 v[76:77], v[2:3], v[2:3]
	v_mov_b64_e32 v[82:83], s[72:73]
	v_pk_fma_f32 v[8:9], v[48:49], v[16:17], v[8:9]
	v_pk_mul_f32 v[16:17], v[6:7], v[6:7]
	v_pk_fma_f32 v[74:75], v[74:75], s[74:75], v[82:83] op_sel_hi:[1,0,0] neg_lo:[1,0,0] neg_hi:[1,0,0]
	v_pk_fma_f32 v[76:77], v[76:77], s[74:75], v[82:83] op_sel_hi:[1,0,0] neg_lo:[1,0,0] neg_hi:[1,0,0]
	v_pk_fma_f32 v[8:9], v[44:45], v[12:13], v[8:9]
	v_pk_fma_f32 v[16:17], v[16:17], s[74:75], v[82:83] op_sel_hi:[1,0,0] neg_lo:[1,0,0] neg_hi:[1,0,0]
	v_pk_mul_f32 v[74:75], v[4:5], v[74:75]
	v_pk_mul_f32 v[76:77], v[2:3], v[76:77]
	v_pk_mul_f32 v[14:15], v[8:9], v[8:9]
	v_pk_mul_f32 v[16:17], v[6:7], v[16:17]
	v_exp_f32_e32 v76, v76
	v_exp_f32_e32 v77, v77
	v_exp_f32_e32 v74, v74
	v_exp_f32_e32 v75, v75
	v_pk_fma_f32 v[14:15], v[14:15], s[74:75], v[82:83] op_sel_hi:[1,0,0] neg_lo:[1,0,0] neg_hi:[1,0,0]
	v_exp_f32_e32 v16, v16
	v_exp_f32_e32 v17, v17
	v_pk_mul_f32 v[14:15], v[8:9], v[14:15]
	v_pk_add_f32 v[74:75], v[74:75], 1.0 op_sel_hi:[1,0]
	v_exp_f32_e32 v14, v14
	v_exp_f32_e32 v15, v15
	v_pk_add_f32 v[76:77], v[76:77], 1.0 op_sel_hi:[1,0]
	v_pk_add_f32 v[16:17], v[16:17], 1.0 op_sel_hi:[1,0]
	v_rcp_f32_e32 v76, v76
	v_rcp_f32_e32 v77, v77
	v_rcp_f32_e32 v74, v74
	v_rcp_f32_e32 v75, v75
	v_rcp_f32_e32 v16, v16
	v_rcp_f32_e32 v17, v17
	v_pk_add_f32 v[14:15], v[14:15], 1.0 op_sel_hi:[1,0]
	v_mov_b32_e32 v219, v218
	v_rcp_f32_e32 v14, v14
	v_rcp_f32_e32 v15, v15
	v_pk_mul_f32 v[38:39], v[38:39], v[218:219]
	v_pk_mul_f32 v[34:35], v[34:35], v[218:219]
	v_pk_mul_f32 v[4:5], v[4:5], v[74:75]
	v_pk_mul_f32 v[2:3], v[2:3], v[76:77]
	v_pk_mul_f32 v[6:7], v[6:7], v[16:17]
	v_pk_mul_f32 v[4:5], v[40:41], v[4:5]
	v_pk_mul_f32 v[2:3], v[38:39], v[2:3]
	v_pk_mul_f32 v[6:7], v[34:35], v[6:7]
	v_pk_mul_f32 v[8:9], v[8:9], v[14:15]
	v_cvt_pk_bf16_f32 v2, v2, v3
	v_cvt_pk_bf16_f32 v3, v4, v5
	v_cvt_pk_bf16_f32 v4, v6, v7
	v_mad_i64_i32 v[6:7], s[88:89], v84, s97, v[216:217]
	v_pk_mul_f32 v[14:15], v[30:31], v[208:209] op_sel_hi:[1,0]
	v_pk_mul_f32 v[8:9], v[36:37], v[8:9]
	v_pk_mul_f32 v[16:17], v[32:33], v[208:209] op_sel_hi:[1,0]
	v_cvt_pk_bf16_f32 v5, v8, v9
	global_store_dwordx4 v[6:7], v[2:5], off nt
	v_pk_mul_f32 v[26:27], v[26:27], v[208:209] op_sel_hi:[1,0]
	v_cndmask_b32_e64 v6, v17, v81, s[8:9]
	v_cndmask_b32_e64 v2, v14, v78, s[6:7]
	v_cndmask_b32_e64 v3, v14, v78, s[8:9]
	v_cndmask_b32_e64 v4, v15, v79, s[8:9]
	v_mov_b32_dpp v30, v2 row_ror:1 row_mask:0xf bank_mask:0xf bound_ctrl:1
	v_mov_b32_dpp v2, v3 row_ror:2 row_mask:0xf bank_mask:0xf bound_ctrl:1
	v_cndmask_b32_e64 v3, v15, v79, s[6:7]
	v_cndmask_b32_e64 v5, v16, v80, s[8:9]
	v_cndmask_b32_e64 v7, v26, v10, s[8:9]
	v_mov_b32_dpp v31, v3 row_ror:1 row_mask:0xf bank_mask:0xf bound_ctrl:1
	v_mov_b32_dpp v3, v4 row_ror:2 row_mask:0xf bank_mask:0xf bound_ctrl:1
	v_cndmask_b32_e64 v4, v16, v80, s[6:7]
	v_pk_mul_f32 v[28:29], v[28:29], v[208:209] op_sel_hi:[1,0]
	v_cndmask_b32_e64 v8, v27, v11, s[8:9]
	v_mov_b32_dpp v32, v4 row_ror:1 row_mask:0xf bank_mask:0xf bound_ctrl:1
	v_mov_b32_dpp v4, v5 row_ror:2 row_mask:0xf bank_mask:0xf bound_ctrl:1
	v_cndmask_b32_e64 v5, v17, v81, s[6:7]
	v_cndmask_b32_e64 v9, v28, v12, s[8:9]
	v_cndmask_b32_e64 v34, v29, v13, s[8:9]
	v_mov_b32_dpp v33, v5 row_ror:1 row_mask:0xf bank_mask:0xf bound_ctrl:1
	v_mov_b32_dpp v5, v6 row_ror:2 row_mask:0xf bank_mask:0xf bound_ctrl:1
	v_cndmask_b32_e64 v6, v26, v10, s[6:7]
	s_and_b64 vcc, exec, s[18:19]
	s_nop 0
	v_mov_b32_dpp v10, v6 row_ror:1 row_mask:0xf bank_mask:0xf bound_ctrl:1
	v_mov_b32_dpp v6, v7 row_ror:2 row_mask:0xf bank_mask:0xf bound_ctrl:1
	v_cndmask_b32_e64 v7, v27, v11, s[6:7]
	s_nop 1
	v_mov_b32_dpp v11, v7 row_ror:1 row_mask:0xf bank_mask:0xf bound_ctrl:1
	v_mov_b32_dpp v7, v8 row_ror:2 row_mask:0xf bank_mask:0xf bound_ctrl:1
	v_cndmask_b32_e64 v8, v28, v12, s[6:7]
	s_nop 1
	v_mov_b32_dpp v12, v8 row_ror:1 row_mask:0xf bank_mask:0xf bound_ctrl:1
	v_mov_b32_dpp v8, v9 row_ror:2 row_mask:0xf bank_mask:0xf bound_ctrl:1
	v_cndmask_b32_e64 v9, v29, v13, s[6:7]
	s_nop 1
	v_mov_b32_dpp v13, v9 row_ror:1 row_mask:0xf bank_mask:0xf bound_ctrl:1
	v_mov_b32_dpp v9, v34 row_ror:2 row_mask:0xf bank_mask:0xf bound_ctrl:1
	s_cbranch_vccnz .LBB0_2773
	v_add_u32_e32 v36, 0xb0, v214
	s_cbranch_execz .LBB0_2774
	s_branch .LBB0_2779

;     __device__ __forceinline__ void operator()(const f32x4 (&acc)[2][2][4][2], const Unit& u, int wr, int wc, int fr, int fq) const {
;     ...
;                     const int s16 = row & 15;
;                     if (s16 >= 14) { float* dst = o_fcs + (size_t)((row >> 4) * 2 + (s16 - 14)) * DFF + col0; *(f32x4*)dst = zc[0]; *(f32x4*)(dst + 4) = zc[1]; }
.LBB0_2777:
	v_ashrrev_i32_e32 v34, 3, v36
	v_and_b32_e32 v34, -2, v34
	v_add_u32_e32 v34, v34, v196
	v_mad_i64_i32 v[34:35], s[88:89], v34, s0, v[210:211]
	global_store_dwordx4 v[34:35], v[14:17], off nt
	global_store_dwordx4 v[34:35], v[26:29], off offset:16 nt

; __device__ __forceinline__ u32x4 pack8(f32x4 a, f32x4 b) { u32x4 w; w.x = cvt_pk_bf16(a[0], a[1]); w.y = cvt_pk_bf16(a[2], a[3]); w.z = cvt_pk_bf16(b[0], b[1]); w.w = cvt_pk_bf16(b[2], b[3]); return w; }
;     __device__ __forceinline__ void operator()(const f32x4 (&acc)[2][2][4][2], const Unit& u, int wr, int wc, int fr, int fq) const {
;     ...
;                 const bool defer = pm != 0 && m == 0 && fr < 2;
;                 if (!defer) { f32x4 a[2];
; #pragma unroll
;                     for (int n = 0; n < 2; ++n)
;                     { const f32x4 g = bb[n] + w0[n] * z2[n] + w1[n] * z1[n] + w2[n] * zc[n]; a[n] = gelu4(g) * vv[n]; }
;                     *(u32x4*)(ACT + (size_t)row * DFF + col0) = pack8(a[0], a[1]);
;                 } else { const size_t o = ((size_t)((row - G_ROWP) >> 6) * 2 + fr) * DFF + col0;
;                     *(f32x4*)(HEADG + o) = zc[0]; *(f32x4*)(HEADG + o + 4) = zc[1]; *(f32x4*)(HEADV + o) = vv[0]; *(f32x4*)(HEADV + o + 4) = vv[1]; }
;                 if (pm != 0 && m == 3 && fr >= 14) { const size_t o = ((size_t)((row - G_ROWP) >> 6) * 2 + (fr - 14)) * DFF + col0; *(f32x4*)(TAILG + o) = zc[0]; *(f32x4*)(TAILG + o + 4) = zc[1]; }
.LBB0_2779:
	v_pk_fma_f32 v[4:5], v[68:69], v[4:5], v[72:73]
	v_pk_fma_f32 v[2:3], v[66:67], v[2:3], v[70:71]
	v_pk_fma_f32 v[6:7], v[50:51], v[6:7], v[54:55]
	v_pk_fma_f32 v[4:5], v[64:65], v[32:33], v[4:5]
	v_pk_fma_f32 v[2:3], v[62:63], v[30:31], v[2:3]
	v_pk_fma_f32 v[6:7], v[46:47], v[10:11], v[6:7]
	v_pk_fma_f32 v[4:5], v[60:61], v[16:17], v[4:5]
	v_pk_fma_f32 v[2:3], v[58:59], v[14:15], v[2:3]
	v_pk_fma_f32 v[8:9], v[52:53], v[8:9], v[56:57]
	v_pk_fma_f32 v[6:7], v[42:43], v[26:27], v[6:7]
	v_pk_mul_f32 v[30:31], v[4:5], v[4:5]
	v_pk_mul_f32 v[32:33], v[2:3], v[2:3]
	v_mov_b64_e32 v[38:39], s[72:73]
	v_pk_fma_f32 v[8:9], v[48:49], v[12:13], v[8:9]
	v_pk_mul_f32 v[12:13], v[6:7], v[6:7]
	v_pk_fma_f32 v[30:31], v[30:31], s[74:75], v[38:39] op_sel_hi:[1,0,0] neg_lo:[1,0,0] neg_hi:[1,0,0]
	v_pk_fma_f32 v[32:33], v[32:33], s[74:75], v[38:39] op_sel_hi:[1,0,0] neg_lo:[1,0,0] neg_hi:[1,0,0]
	v_pk_fma_f32 v[8:9], v[44:45], v[28:29], v[8:9]
	v_pk_fma_f32 v[12:13], v[12:13], s[74:75], v[38:39] op_sel_hi:[1,0,0] neg_lo:[1,0,0] neg_hi:[1,0,0]
	v_pk_mul_f32 v[30:31], v[4:5], v[30:31]
	v_pk_mul_f32 v[32:33], v[2:3], v[32:33]
	v_pk_mul_f32 v[10:11], v[8:9], v[8:9]
	v_pk_mul_f32 v[12:13], v[6:7], v[12:13]
	v_exp_f32_e32 v32, v32
	v_exp_f32_e32 v30, v30
	v_exp_f32_e32 v31, v31
	v_exp_f32_e32 v33, v33
	v_pk_fma_f32 v[10:11], v[10:11], s[74:75], v[38:39] op_sel_hi:[1,0,0] neg_lo:[1,0,0] neg_hi:[1,0,0]
	v_exp_f32_e32 v12, v12
	v_exp_f32_e32 v13, v13
	v_pk_mul_f32 v[10:11], v[8:9], v[10:11]
	v_pk_add_f32 v[30:31], v[30:31], 1.0 op_sel_hi:[1,0]
	v_exp_f32_e32 v10, v10
	v_exp_f32_e32 v11, v11
	v_pk_add_f32 v[32:33], v[32:33], 1.0 op_sel_hi:[1,0]
	v_pk_add_f32 v[12:13], v[12:13], 1.0 op_sel_hi:[1,0]
	v_rcp_f32_e32 v32, v32
	v_rcp_f32_e32 v33, v33
	v_rcp_f32_e32 v30, v30
	v_rcp_f32_e32 v31, v31
	v_rcp_f32_e32 v12, v12
	v_rcp_f32_e32 v13, v13
	v_pk_add_f32 v[10:11], v[10:11], 1.0 op_sel_hi:[1,0]
	v_mov_b32_e32 v209, v208
	v_rcp_f32_e32 v10, v10
	v_rcp_f32_e32 v11, v11
	v_mov_b32_e32 v34, v208
	v_mov_b32_e32 v35, v208
	v_pk_mul_f32 v[24:25], v[24:25], v[34:35]
	v_pk_mul_f32 v[22:23], v[22:23], v[208:209]
	v_pk_mul_f32 v[18:19], v[18:19], v[208:209]
	v_pk_mul_f32 v[4:5], v[4:5], v[30:31]
	v_pk_mul_f32 v[2:3], v[2:3], v[32:33]
	v_pk_mul_f32 v[6:7], v[6:7], v[12:13]
	v_pk_mul_f32 v[4:5], v[24:25], v[4:5]
	v_pk_mul_f32 v[2:3], v[22:23], v[2:3]
	v_pk_mul_f32 v[6:7], v[18:19], v[6:7]
	v_pk_mul_f32 v[20:21], v[20:21], v[34:35]
	v_pk_mul_f32 v[8:9], v[8:9], v[10:11]
	v_cvt_pk_bf16_f32 v2, v2, v3
	v_cvt_pk_bf16_f32 v3, v4, v5
	v_cvt_pk_bf16_f32 v4, v6, v7
	v_mad_i64_i32 v[6:7], s[18:19], v36, s97, v[216:217]
	v_pk_mul_f32 v[8:9], v[20:21], v[8:9]
	s_nop 0
	v_cvt_pk_bf16_f32 v5, v8, v9
	global_store_dwordx4 v[6:7], v[2:5], off nt
	s_and_saveexec_b64 s[18:19], s[86:87]
	s_cbranch_execz .LBB0_2781
	v_lshl_add_u64 v[2:3], s[84:85], 0, v[196:197]
	v_mad_u64_u32 v[4:5], s[84:85], v2, s0, v[114:115]
	v_mad_i32_i24 v5, v3, s0, v5
	global_store_dwordx4 v[4:5], v[14:17], off nt
	global_store_dwordx4 v[4:5], v[26:29], off offset:16 nt

; #define GAS __attribute__((address_space(1)))
; #define LAS __attribute__((address_space(3)))
; __device__ __forceinline__ unsigned pk2(float lo, float hi) { return pg8::cvt_pk_bf16(lo, hi); }
; #define LDS_WAIT() asm volatile("s_waitcnt lgkmcnt(0)" ::: "memory")
; __device__ __forceinline__ void tr_store(const TrItem& t, const float (&tv)[32], LAS float* scr, int lane) {
;     const float* gp = t.gk ? t.gk + t.k0 + 32 * (lane >> 5) : nullptr; LAS unsigned* T = (LAS unsigned*)scr;
; #pragma unroll
;     for (int j = 0; j < 16; ++j) { float a = tv[2 * j], b = tv[2 * j + 1]; if (gp) { a *= gp[2 * j]; b *= gp[2 * j + 1]; } T[(16 * (lane >> 5) + j) * TR_P + (lane & 31)] = pk2(a, b); }
;     LDS_WAIT(); asm volatile("" ::: "memory");
;     const int c = lane & 7;
; #pragma unroll
;     for (int j = 0; j < 4; ++j) { const int n = (lane >> 3) + 8 * j; const LAS unsigned* s = T + (4 * c) * TR_P + n;
;         v4u o; o.x = s[0 * TR_P]; o.y = s[1 * TR_P]; o.z = s[2 * TR_P]; o.w = s[3 * TR_P];
;         *(GAS v4u*)(t.WT + (size_t)(t.drow + n) * t.K + t.k0 + 8 * c) = o; }
;     LDS_WAIT(); asm volatile("" ::: "memory");
; }
.LBB0_2974:
	s_nop 0
	v_cvt_pk_bf16_f32 v4, v76, v77
	ds_write_b32 v82, v4
	s_waitcnt lgkmcnt(0)
	ds_read2_b32 v[88:89], v7 offset1:8
	ds_read2_b32 v[74:75], v7 offset0:34 offset1:42
	ds_read2_b32 v[90:91], v7 offset0:68 offset1:76
	ds_read2_b32 v[76:77], v7 offset0:102 offset1:110
	v_add_u32_e32 v4, s68, v3
	v_mad_i64_i32 v[92:93], s[10:11], s67, v4, 0
	v_lshl_add_u64 v[92:93], v[92:93], 1, s[50:51]
	s_lshl_b64 s[10:11], s[48:49], 1
	v_lshl_add_u64 v[92:93], v[92:93], 0, s[10:11]
	v_lshlrev_b32_e32 v4, 1, v6
	s_waitcnt lgkmcnt(3)
	v_mov_b32_e32 v84, v88
	s_waitcnt lgkmcnt(2)
	v_mov_b32_e32 v85, v74
	s_waitcnt lgkmcnt(1)
	v_mov_b32_e32 v86, v90
	s_waitcnt lgkmcnt(0)
	v_mov_b32_e32 v87, v76
	v_lshl_add_u64 v[92:93], v[92:93], 0, v[4:5]
	v_add_u32_e32 v73, s68, v78
	global_store_dwordx4 v[92:93], v[84:87], off nt
	v_mov_b32_e32 v74, v89
	v_mov_b32_e32 v76, v91
	v_mad_i64_i32 v[84:85], s[64:65], s67, v73, 0
	v_lshl_add_u64 v[84:85], v[84:85], 1, s[50:51]
	v_lshl_add_u64 v[84:85], v[84:85], 0, s[10:11]
	v_lshl_add_u64 v[88:89], v[84:85], 0, v[4:5]
	ds_read2_b32 v[90:91], v7 offset0:16 offset1:24
	ds_read2_b32 v[84:85], v7 offset0:50 offset1:58
	ds_read2_b32 v[92:93], v7 offset0:84 offset1:92
	ds_read2_b32 v[86:87], v7 offset0:118 offset1:126
	v_add_u32_e32 v73, s68, v79
	global_store_dwordx4 v[88:89], v[74:77], off nt
	v_mad_i64_i32 v[88:89], s[64:65], s67, v73, 0
	v_lshl_add_u64 v[88:89], v[88:89], 1, s[50:51]
	v_lshl_add_u64 v[88:89], v[88:89], 0, s[10:11]
	s_waitcnt lgkmcnt(3)
	v_mov_b32_e32 v74, v90
	s_waitcnt lgkmcnt(2)
	v_mov_b32_e32 v75, v84
	s_waitcnt lgkmcnt(1)
	v_mov_b32_e32 v76, v92
	s_waitcnt lgkmcnt(0)
	v_mov_b32_e32 v77, v86
	v_lshl_add_u64 v[88:89], v[88:89], 0, v[4:5]
	v_add_u32_e32 v73, s68, v80
	global_store_dwordx4 v[88:89], v[74:77], off nt
	v_mov_b32_e32 v84, v91
	v_mov_b32_e32 v86, v93
	v_mad_i64_i32 v[74:75], s[64:65], s67, v73, 0
	v_lshl_add_u64 v[74:75], v[74:75], 1, s[50:51]
	v_lshl_add_u64 v[74:75], v[74:75], 0, s[10:11]
	v_lshl_add_u64 v[74:75], v[74:75], 0, v[4:5]
	global_store_dwordx4 v[74:75], v[84:87], off nt
	s_waitcnt lgkmcnt(0)
	s_and_b64 vcc, exec, s[8:9]
	s_mov_b64 s[10:11], -1
	s_cbranch_vccnz .LBB0_2872
	s_add_i32 s47, s41, 0xe002
	s_cmp_lt_u32 s71, 14
	s_cselect_b64 s[8:9], -1, 0
	s_cmp_lt_i32 s47, 0x14000
	s_cselect_b64 s[10:11], -1, 0
	s_and_b64 s[8:9], s[8:9], s[10:11]
	s_xor_b64 s[10:11], s[8:9], -1
	s_and_b64 vcc, exec, s[10:11]
	s_cbranch_vccnz .LBB0_2984
	s_cmpk_gt_i32 s47, 0x1fff
	s_cbranch_scc0 .LBB0_2982
	s_cmpk_gt_u32 s47, 0xdfff
	s_cbranch_scc0 .LBB0_3079
	s_add_i32 s41, s41, 2
	s_lshr_b32 s38, s41, 1
	s_and_b32 s48, s38, 0x7fffffc0
	s_add_i32 s38, s70, 0x1c0040
	s_and_b32 s66, s38, 0xfe0
	s_mov_b64 s[42:43], 0
	s_mov_b64 s[38:39], s[24:25]
	s_cbranch_execz .LBB0_3080
	s_movk_i32 s52, 0x1000
	s_movk_i32 s67, 0x3000
	s_mov_b64 s[50:51], s[34:35]
	s_mov_b32 s68, s66
	s_cbranch_execz .LBB0_2983
	s_branch .LBB0_2984

; #define GAS __attribute__((address_space(1)))
; #define LAS __attribute__((address_space(3)))
; __device__ __forceinline__ unsigned pk2(float lo, float hi) { return pg8::cvt_pk_bf16(lo, hi); }
; #define LDS_WAIT() asm volatile("s_waitcnt lgkmcnt(0)" ::: "memory")
; __device__ __forceinline__ void tr_store(const TrItem& t, const float (&tv)[32], LAS float* scr, int lane) {
;     const float* gp = t.gk ? t.gk + t.k0 + 32 * (lane >> 5) : nullptr; LAS unsigned* T = (LAS unsigned*)scr;
; #pragma unroll
;     for (int j = 0; j < 16; ++j) { float a = tv[2 * j], b = tv[2 * j + 1]; if (gp) { a *= gp[2 * j]; b *= gp[2 * j + 1]; } T[(16 * (lane >> 5) + j) * TR_P + (lane & 31)] = pk2(a, b); }
;     LDS_WAIT(); asm volatile("" ::: "memory");
;     const int c = lane & 7;
; #pragma unroll
;     for (int j = 0; j < 4; ++j) { const int n = (lane >> 3) + 8 * j; const LAS unsigned* s = T + (4 * c) * TR_P + n;
;         v4u o; o.x = s[0 * TR_P]; o.y = s[1 * TR_P]; o.z = s[2 * TR_P]; o.w = s[3 * TR_P];
;         *(GAS v4u*)(t.WT + (size_t)(t.drow + n) * t.K + t.k0 + 8 * c) = o; }
;     LDS_WAIT(); asm volatile("" ::: "memory");
; }
.LBB0_3078:
	s_nop 0
	v_cvt_pk_bf16_f32 v72, v74, v75
	ds_write_b32 v82, v72
	s_waitcnt lgkmcnt(0)
	ds_read2_b32 v[76:77], v7 offset1:8
	ds_read2_b32 v[72:73], v7 offset0:34 offset1:42
	ds_read2_b32 v[88:89], v7 offset0:68 offset1:76
	ds_read2_b32 v[74:75], v7 offset0:102 offset1:110
	s_add_i32 s70, s70, 64
	s_waitcnt lgkmcnt(3)
	v_mov_b32_e32 v84, v76
	s_waitcnt lgkmcnt(2)
	v_mov_b32_e32 v85, v72
	v_add_u32_e32 v72, s63, v3
	v_mad_i64_i32 v[90:91], s[8:9], s62, v72, 0
	v_lshl_add_u64 v[90:91], v[90:91], 1, s[44:45]
	s_lshl_b64 s[8:9], s[40:41], 1
	v_add_u32_e32 v76, s63, v78
	v_lshl_add_u64 v[90:91], v[90:91], 0, s[8:9]
	v_mov_b32_e32 v72, v77
	v_mad_i64_i32 v[76:77], s[64:65], s62, v76, 0
	s_waitcnt lgkmcnt(1)
	v_mov_b32_e32 v86, v88
	s_waitcnt lgkmcnt(0)
	v_mov_b32_e32 v87, v74
	v_lshl_add_u64 v[90:91], v[90:91], 0, v[4:5]
	v_lshl_add_u64 v[76:77], v[76:77], 1, s[44:45]
	global_store_dwordx4 v[90:91], v[84:87], off nt
	v_lshl_add_u64 v[76:77], v[76:77], 0, s[8:9]
	v_mov_b32_e32 v74, v89
	v_lshl_add_u64 v[76:77], v[76:77], 0, v[4:5]
	ds_read2_b32 v[88:89], v7 offset0:16 offset1:24
	ds_read2_b32 v[84:85], v7 offset0:50 offset1:58
	ds_read2_b32 v[90:91], v7 offset0:84 offset1:92
	ds_read2_b32 v[86:87], v7 offset0:118 offset1:126
	global_store_dwordx4 v[76:77], v[72:75], off nt
	v_add_u32_e32 v76, s63, v79
	v_mad_i64_i32 v[76:77], s[64:65], s62, v76, 0
	v_lshl_add_u64 v[76:77], v[76:77], 1, s[44:45]
	v_lshl_add_u64 v[76:77], v[76:77], 0, s[8:9]
	s_waitcnt lgkmcnt(3)
	v_mov_b32_e32 v72, v88
	s_waitcnt lgkmcnt(2)
	v_mov_b32_e32 v73, v84
	s_waitcnt lgkmcnt(1)
	v_mov_b32_e32 v74, v90
	s_waitcnt lgkmcnt(0)
	v_mov_b32_e32 v75, v86
	v_lshl_add_u64 v[76:77], v[76:77], 0, v[4:5]
	global_store_dwordx4 v[76:77], v[72:75], off nt
	v_mov_b32_e32 v84, v89
	v_mov_b32_e32 v86, v91
	v_add_u32_e32 v72, s63, v80
	v_mad_i64_i32 v[72:73], s[64:65], s62, v72, 0
	v_lshl_add_u64 v[72:73], v[72:73], 1, s[44:45]
	v_lshl_add_u64 v[72:73], v[72:73], 0, s[8:9]
	v_lshl_add_u64 v[72:73], v[72:73], 0, v[4:5]
	global_store_dwordx4 v[72:73], v[84:87], off nt
	s_waitcnt lgkmcnt(0)
	s_add_i32 s71, s71, 2
	s_and_b64 vcc, exec, s[10:11]
	s_cbranch_vccz .LBB0_2873
	s_branch .LBB0_2795

; #define GAS __attribute__((address_space(1)))
; #define LAS __attribute__((address_space(3)))
; __device__ __forceinline__ unsigned pk2(float lo, float hi) { return pg8::cvt_pk_bf16(lo, hi); }
; #define LDS_WAIT() asm volatile("s_waitcnt lgkmcnt(0)" ::: "memory")
; __device__ __forceinline__ void tr_store(const TrItem& t, const float (&tv)[32], LAS float* scr, int lane) {
;     const float* gp = t.gk ? t.gk + t.k0 + 32 * (lane >> 5) : nullptr; LAS unsigned* T = (LAS unsigned*)scr;
; #pragma unroll
;     for (int j = 0; j < 16; ++j) { float a = tv[2 * j], b = tv[2 * j + 1]; if (gp) { a *= gp[2 * j]; b *= gp[2 * j + 1]; } T[(16 * (lane >> 5) + j) * TR_P + (lane & 31)] = pk2(a, b); }
;     LDS_WAIT(); asm volatile("" ::: "memory");
;     const int c = lane & 7;
; #pragma unroll
;     for (int j = 0; j < 4; ++j) { const int n = (lane >> 3) + 8 * j; const LAS unsigned* s = T + (4 * c) * TR_P + n;
;         v4u o; o.x = s[0 * TR_P]; o.y = s[1 * TR_P]; o.z = s[2 * TR_P]; o.w = s[3 * TR_P];
;         *(GAS v4u*)(t.WT + (size_t)(t.drow + n) * t.K + t.k0 + 8 * c) = o; }
;     LDS_WAIT(); asm volatile("" ::: "memory");
; }
.LBB0_3316:
	s_nop 0
	v_cvt_pk_bf16_f32 v4, v76, v77
	ds_write_b32 v82, v4
	s_waitcnt lgkmcnt(0)
	ds_read2_b32 v[88:89], v7 offset1:8
	ds_read2_b32 v[74:75], v7 offset0:34 offset1:42
	ds_read2_b32 v[90:91], v7 offset0:68 offset1:76
	ds_read2_b32 v[76:77], v7 offset0:102 offset1:110
	v_add_u32_e32 v4, s71, v3
	v_mad_i64_i32 v[92:93], s[10:11], s70, v4, 0
	v_lshl_add_u64 v[92:93], v[92:93], 1, s[54:55]
	s_lshl_b64 s[10:11], s[52:53], 1
	v_lshl_add_u64 v[92:93], v[92:93], 0, s[10:11]
	v_lshlrev_b32_e32 v4, 1, v6
	s_waitcnt lgkmcnt(3)
	v_mov_b32_e32 v84, v88
	s_waitcnt lgkmcnt(2)
	v_mov_b32_e32 v85, v74
	s_waitcnt lgkmcnt(1)
	v_mov_b32_e32 v86, v90
	s_waitcnt lgkmcnt(0)
	v_mov_b32_e32 v87, v76
	v_lshl_add_u64 v[92:93], v[92:93], 0, v[4:5]
	v_add_u32_e32 v73, s71, v78
	global_store_dwordx4 v[92:93], v[84:87], off nt
	v_mov_b32_e32 v74, v89
	v_mov_b32_e32 v76, v91
	v_mad_i64_i32 v[84:85], s[68:69], s70, v73, 0
	v_lshl_add_u64 v[84:85], v[84:85], 1, s[54:55]
	v_lshl_add_u64 v[84:85], v[84:85], 0, s[10:11]
	v_lshl_add_u64 v[88:89], v[84:85], 0, v[4:5]
	ds_read2_b32 v[90:91], v7 offset0:16 offset1:24
	ds_read2_b32 v[84:85], v7 offset0:50 offset1:58
	ds_read2_b32 v[92:93], v7 offset0:84 offset1:92
	ds_read2_b32 v[86:87], v7 offset0:118 offset1:126
	v_add_u32_e32 v73, s71, v79
	global_store_dwordx4 v[88:89], v[74:77], off nt
	v_mad_i64_i32 v[88:89], s[68:69], s70, v73, 0
	v_lshl_add_u64 v[88:89], v[88:89], 1, s[54:55]
	v_lshl_add_u64 v[88:89], v[88:89], 0, s[10:11]
	s_waitcnt lgkmcnt(3)
	v_mov_b32_e32 v74, v90
	s_waitcnt lgkmcnt(2)
	v_mov_b32_e32 v75, v84
	s_waitcnt lgkmcnt(1)
	v_mov_b32_e32 v76, v92
	s_waitcnt lgkmcnt(0)
	v_mov_b32_e32 v77, v86
	v_lshl_add_u64 v[88:89], v[88:89], 0, v[4:5]
	v_add_u32_e32 v73, s71, v80
	global_store_dwordx4 v[88:89], v[74:77], off nt
	v_mov_b32_e32 v84, v91
	v_mov_b32_e32 v86, v93
	v_mad_i64_i32 v[74:75], s[68:69], s70, v73, 0
	v_lshl_add_u64 v[74:75], v[74:75], 1, s[54:55]
	v_lshl_add_u64 v[74:75], v[74:75], 0, s[10:11]
	v_lshl_add_u64 v[74:75], v[74:75], 0, v[4:5]
	global_store_dwordx4 v[74:75], v[84:87], off nt
	s_waitcnt lgkmcnt(0)
	s_and_b64 vcc, exec, s[8:9]
	s_mov_b64 s[10:11], -1
	s_cbranch_vccnz .LBB0_3214
	s_add_i32 s51, s45, 0xe002
	s_cmp_lt_u32 s74, 14
	s_cselect_b64 s[8:9], -1, 0
	s_cmp_lt_i32 s51, 0x14000
	s_cselect_b64 s[10:11], -1, 0
	s_and_b64 s[8:9], s[8:9], s[10:11]
	s_xor_b64 s[10:11], s[8:9], -1
	s_and_b64 vcc, exec, s[10:11]
	s_cbranch_vccnz .LBB0_3326
	s_cmpk_gt_i32 s51, 0x1fff
	s_cbranch_scc0 .LBB0_3324
	s_cmpk_gt_u32 s51, 0xdfff
	s_cbranch_scc0 .LBB0_3421
	s_add_i32 s45, s45, 2
	s_lshr_b32 s42, s45, 1
	s_and_b32 s52, s42, 0x7fffffc0
	s_add_i32 s42, s73, 0x1c0040
	s_and_b32 s63, s42, 0xfe0
	s_mov_b64 s[46:47], 0
	s_mov_b64 s[42:43], s[30:31]
	s_cbranch_execz .LBB0_3422
	s_movk_i32 s64, 0x1000
	s_movk_i32 s70, 0x3000
	s_mov_b64 s[54:55], s[38:39]
	s_mov_b32 s71, s63
	s_cbranch_execz .LBB0_3325
	s_branch .LBB0_3326

; #define GAS __attribute__((address_space(1)))
; #define LAS __attribute__((address_space(3)))
; __device__ __forceinline__ unsigned pk2(float lo, float hi) { return pg8::cvt_pk_bf16(lo, hi); }
; #define LDS_WAIT() asm volatile("s_waitcnt lgkmcnt(0)" ::: "memory")
; __device__ __forceinline__ void tr_store(const TrItem& t, const float (&tv)[32], LAS float* scr, int lane) {
;     const float* gp = t.gk ? t.gk + t.k0 + 32 * (lane >> 5) : nullptr; LAS unsigned* T = (LAS unsigned*)scr;
; #pragma unroll
;     for (int j = 0; j < 16; ++j) { float a = tv[2 * j], b = tv[2 * j + 1]; if (gp) { a *= gp[2 * j]; b *= gp[2 * j + 1]; } T[(16 * (lane >> 5) + j) * TR_P + (lane & 31)] = pk2(a, b); }
;     LDS_WAIT(); asm volatile("" ::: "memory");
;     const int c = lane & 7;
; #pragma unroll
;     for (int j = 0; j < 4; ++j) { const int n = (lane >> 3) + 8 * j; const LAS unsigned* s = T + (4 * c) * TR_P + n;
;         v4u o; o.x = s[0 * TR_P]; o.y = s[1 * TR_P]; o.z = s[2 * TR_P]; o.w = s[3 * TR_P];
;         *(GAS v4u*)(t.WT + (size_t)(t.drow + n) * t.K + t.k0 + 8 * c) = o; }
;     LDS_WAIT(); asm volatile("" ::: "memory");
; }
.LBB0_3420:
	s_nop 0
	v_cvt_pk_bf16_f32 v72, v74, v75
	ds_write_b32 v82, v72
	s_waitcnt lgkmcnt(0)
	ds_read2_b32 v[76:77], v7 offset1:8
	ds_read2_b32 v[72:73], v7 offset0:34 offset1:42
	ds_read2_b32 v[88:89], v7 offset0:68 offset1:76
	ds_read2_b32 v[74:75], v7 offset0:102 offset1:110
	s_add_i32 s73, s73, 64
	s_waitcnt lgkmcnt(3)
	v_mov_b32_e32 v84, v76
	s_waitcnt lgkmcnt(2)
	v_mov_b32_e32 v85, v72
	v_add_u32_e32 v72, s62, v3
	v_mad_i64_i32 v[90:91], s[8:9], s61, v72, 0
	v_lshl_add_u64 v[90:91], v[90:91], 1, s[48:49]
	s_lshl_b64 s[8:9], s[44:45], 1
	v_add_u32_e32 v76, s62, v78
	v_lshl_add_u64 v[90:91], v[90:91], 0, s[8:9]
	v_mov_b32_e32 v72, v77
	v_mad_i64_i32 v[76:77], s[68:69], s61, v76, 0
	s_waitcnt lgkmcnt(1)
	v_mov_b32_e32 v86, v88
	s_waitcnt lgkmcnt(0)
	v_mov_b32_e32 v87, v74
	v_lshl_add_u64 v[90:91], v[90:91], 0, v[4:5]
	v_lshl_add_u64 v[76:77], v[76:77], 1, s[48:49]
	global_store_dwordx4 v[90:91], v[84:87], off nt
	v_lshl_add_u64 v[76:77], v[76:77], 0, s[8:9]
	v_mov_b32_e32 v74, v89
	v_lshl_add_u64 v[76:77], v[76:77], 0, v[4:5]
	ds_read2_b32 v[88:89], v7 offset0:16 offset1:24
	ds_read2_b32 v[84:85], v7 offset0:50 offset1:58
	ds_read2_b32 v[90:91], v7 offset0:84 offset1:92
	ds_read2_b32 v[86:87], v7 offset0:118 offset1:126
	global_store_dwordx4 v[76:77], v[72:75], off nt
	v_add_u32_e32 v76, s62, v79
	v_mad_i64_i32 v[76:77], s[68:69], s61, v76, 0
	v_lshl_add_u64 v[76:77], v[76:77], 1, s[48:49]
	v_lshl_add_u64 v[76:77], v[76:77], 0, s[8:9]
	s_waitcnt lgkmcnt(3)
	v_mov_b32_e32 v72, v88
	s_waitcnt lgkmcnt(2)
	v_mov_b32_e32 v73, v84
	s_waitcnt lgkmcnt(1)
	v_mov_b32_e32 v74, v90
	s_waitcnt lgkmcnt(0)
	v_mov_b32_e32 v75, v86
	v_lshl_add_u64 v[76:77], v[76:77], 0, v[4:5]
	global_store_dwordx4 v[76:77], v[72:75], off nt
	v_mov_b32_e32 v84, v89
	v_mov_b32_e32 v86, v91
	v_add_u32_e32 v72, s62, v80
	v_mad_i64_i32 v[72:73], s[68:69], s61, v72, 0
	v_lshl_add_u64 v[72:73], v[72:73], 1, s[48:49]
	v_lshl_add_u64 v[72:73], v[72:73], 0, s[8:9]
	v_lshl_add_u64 v[72:73], v[72:73], 0, v[4:5]
	global_store_dwordx4 v[72:73], v[84:87], off nt
	s_waitcnt lgkmcnt(0)
	s_add_i32 s74, s74, 2
	s_and_b64 vcc, exec, s[10:11]
	s_cbranch_vccz .LBB0_3215
	s_branch .LBB0_3137
